# combined: attention K-fragment and bias LDS reads batched per pass, FF1 mainloop LDS-DMA issue balanced 4/4/4/4 across phases, per-phase s_setprio flips dropped in the three hot GEMM loops
# speedup vs baseline: 1.0073x; 1.0073x over previous
; __device__ __forceinline__ unsigned pk2(float lo, float hi) { const f32x2 v = {lo, hi}; return __builtin_bit_cast(unsigned, __builtin_convertvector(v, bf16x2_t)); }
; __device__ __forceinline__ void unpack8(u32x4 w, float* f) { f[0] = bflo(w.x); f[1] = bfhi(w.x); f[2] = bflo(w.y); f[3] = bfhi(w.y); f[4] = bflo(w.z); f[5] = bfhi(w.z); f[6] = bflo(w.w); f[7] = bfhi(w.w); }
; __device__ __forceinline__ void attn_phase(CArgs a, int l, LAS unsigned char* lds, int tid, int lane, int wave, int G, int bx) {
;     ...
;                 for (int st = 0; st < 4; ++st) unpack8(qraw[st], qv[st]);
;                 if (hh == 0) {
; #pragma unroll
;                     for (int st = 0; st < 4; ++st) qraw[st] = *(const u32x4*)(PROJ + (size_t)qtok * NPJ + (h + 1) * 64 + st * 16 + hf * 8); }
; #pragma unroll
;                 for (int st = 0; st < 4; ++st) {
; #pragma unroll
;                     for (int j = 0; j < 8; ++j) ss += qv[st][j] * qv[st][j]; }
;                 ss += __shfl_xor(ss, 32);
;                 const float rs = rsqrtf(ss * (1.0f / 64.0f) + EPS) * 0.125f;
; #pragma unroll
;                 for (int st = 0; st < 4; ++st) { const float* qg = a->in[22] + ll * 64 + st * 16 + hf * 8; u32x4 w;
;                     w.x = pk2(qv[st][0] * rs * qg[0], qv[st][1] * rs * qg[1]); w.y = pk2(qv[st][2] * rs * qg[2], qv[st][3] * rs * qg[3]);
;                     w.z = pk2(qv[st][4] * rs * qg[4], qv[st][5] * rs * qg[5]); w.w = pk2(qv[st][6] * rs * qg[6], qv[st][7] * rs * qg[7]);
;                     qf[st] = __builtin_bit_cast(bf16x8, w); } }
;             const float sink = a->in[24][ll * 16 + h]; float mx = sink, sum = 0.f;
.LBB0_359:
	v_lshlrev_b32_e32 v16, 16, v12
	v_and_b32_e32 v17, 0xffff0000, v12
	v_lshlrev_b32_e32 v12, 16, v13
	v_and_b32_e32 v13, 0xffff0000, v13
	v_lshlrev_b32_e32 v32, 16, v0
	v_and_b32_e32 v33, 0xffff0000, v0
	v_lshlrev_b32_e32 v34, 16, v1
	v_and_b32_e32 v35, 0xffff0000, v1
	v_pk_mul_f32 v[0:1], v[16:17], v[16:17]
	v_lshlrev_b32_e32 v36, 16, v2
	v_and_b32_e32 v37, 0xffff0000, v2
	v_lshlrev_b32_e32 v38, 16, v3
	v_and_b32_e32 v39, 0xffff0000, v3
	v_pk_mul_f32 v[2:3], v[12:13], v[12:13]
	v_add_f32_e32 v0, v0, v1
	v_lshlrev_b32_e32 v18, 16, v14
	v_and_b32_e32 v19, 0xffff0000, v14
	v_add_f32_e32 v0, v2, v0
	v_lshlrev_b32_e32 v24, 16, v4
	v_and_b32_e32 v25, 0xffff0000, v4
	v_lshlrev_b32_e32 v26, 16, v5
	v_and_b32_e32 v27, 0xffff0000, v5
	v_pk_mul_f32 v[4:5], v[18:19], v[18:19]
	v_add_f32_e32 v0, v3, v0
	v_lshlrev_b32_e32 v14, 16, v15
	v_and_b32_e32 v15, 0xffff0000, v15
	v_add_f32_e32 v0, v4, v0
	v_lshlrev_b32_e32 v28, 16, v6
	v_and_b32_e32 v29, 0xffff0000, v6
	v_lshlrev_b32_e32 v30, 16, v7
	v_and_b32_e32 v31, 0xffff0000, v7
	v_pk_mul_f32 v[6:7], v[14:15], v[14:15]
	v_add_f32_e32 v0, v5, v0
	v_lshlrev_b32_e32 v20, 16, v8
	v_and_b32_e32 v21, 0xffff0000, v8
	v_add_f32_e32 v0, v6, v0
	v_pk_mul_f32 v[40:41], v[20:21], v[20:21]
	v_add_f32_e32 v0, v7, v0
	v_lshlrev_b32_e32 v8, 16, v9
	v_and_b32_e32 v9, 0xffff0000, v9
	v_add_f32_e32 v0, v40, v0
	v_pk_mul_f32 v[42:43], v[8:9], v[8:9]
	v_add_f32_e32 v0, v41, v0
	v_lshlrev_b32_e32 v22, 16, v10
	v_and_b32_e32 v23, 0xffff0000, v10
	v_add_f32_e32 v0, v42, v0
	v_pk_mul_f32 v[44:45], v[22:23], v[22:23]
	v_add_f32_e32 v0, v43, v0
	v_lshlrev_b32_e32 v10, 16, v11
	v_and_b32_e32 v11, 0xffff0000, v11
	v_add_f32_e32 v0, v44, v0
	v_pk_mul_f32 v[46:47], v[10:11], v[10:11]
	v_add_f32_e32 v0, v45, v0
	v_add_f32_e32 v0, v46, v0
	v_pk_mul_f32 v[48:49], v[24:25], v[24:25]
	v_add_f32_e32 v0, v47, v0
	v_add_f32_e32 v0, v48, v0
	v_pk_mul_f32 v[50:51], v[26:27], v[26:27]
	v_add_f32_e32 v0, v49, v0
	v_add_f32_e32 v0, v50, v0
	v_pk_mul_f32 v[52:53], v[28:29], v[28:29]
	v_add_f32_e32 v0, v51, v0
	v_add_f32_e32 v0, v52, v0
	v_pk_mul_f32 v[54:55], v[30:31], v[30:31]
	v_add_f32_e32 v0, v53, v0
	v_add_f32_e32 v0, v54, v0
	v_pk_mul_f32 v[56:57], v[32:33], v[32:33]
	v_add_f32_e32 v0, v55, v0
	v_add_f32_e32 v0, v56, v0
	v_pk_mul_f32 v[58:59], v[34:35], v[34:35]
	v_add_f32_e32 v0, v57, v0
	v_add_f32_e32 v0, v58, v0
	v_pk_mul_f32 v[60:61], v[36:37], v[36:37]
	v_add_f32_e32 v0, v59, v0
	v_add_f32_e32 v0, v60, v0
	v_pk_mul_f32 v[62:63], v[38:39], v[38:39]
	v_add_f32_e32 v0, v61, v0
	v_add_f32_e32 v0, v62, v0
	v_add_f32_e32 v0, v63, v0
	ds_bpermute_b32 v1, v171, v0
	v_readlane_b32 s2, v255, 29
	s_or_b32 s2, s90, s2
	s_add_i32 s90, s2, s33
	v_lshl_add_u32 v229, s2, 10, v227
	s_waitcnt lgkmcnt(0)
	v_add_f32_e32 v0, v0, v1
	v_fmamk_f32 v0, v0, 0x3c800000, v162
	v_cmp_gt_f32_e32 vcc, s91, v0
	v_mul_f32_e32 v1, 0x4b800000, v0
	s_ashr_i32 s91, s90, 31
	v_cndmask_b32_e32 v0, v0, v1, vcc
	v_rsq_f32_e32 v0, v0
	s_lshl_b64 s[90:91], s[90:91], 2
	s_add_u32 s90, s86, s90
	s_addc_u32 s91, s87, s91
	v_mul_f32_e32 v1, 0x45800000, v0
	v_cndmask_b32_e32 v0, v0, v1, vcc
	v_mul_f32_e32 v40, 0x3e000000, v0
	global_load_dwordx4 v[0:3], v[174:175], off offset:16
	global_load_dwordx4 v[4:7], v[174:175], off
	v_pk_mul_f32 v[16:17], v[40:41], v[16:17] op_sel_hi:[0,1]
	v_add_u32_e32 v230, 0x3000, v153
	s_waitcnt vmcnt(0)
	v_pk_mul_f32 v[4:5], v[4:5], v[16:17]
	s_nop 0
	v_cvt_pk_bf16_f32 v138, v4, v5
	v_pk_mul_f32 v[4:5], v[40:41], v[12:13] op_sel_hi:[0,1]
	v_pk_mul_f32 v[4:5], v[6:7], v[4:5]
	v_pk_mul_f32 v[12:13], v[40:41], v[20:21] op_sel_hi:[0,1]
	v_cvt_pk_bf16_f32 v139, v4, v5
	v_pk_mul_f32 v[4:5], v[40:41], v[18:19] op_sel_hi:[0,1]
	v_pk_mul_f32 v[0:1], v[0:1], v[4:5]
	s_nop 0
	v_cvt_pk_bf16_f32 v140, v0, v1
	v_pk_mul_f32 v[0:1], v[40:41], v[14:15] op_sel_hi:[0,1]
	v_pk_mul_f32 v[0:1], v[2:3], v[0:1]
	s_nop 0
	v_cvt_pk_bf16_f32 v141, v0, v1
	global_load_dwordx4 v[0:3], v[174:175], off offset:80
	global_load_dwordx4 v[4:7], v[174:175], off offset:64
	s_waitcnt vmcnt(0)
	v_pk_mul_f32 v[4:5], v[4:5], v[12:13]
	s_nop 0
	v_cvt_pk_bf16_f32 v142, v4, v5
	v_pk_mul_f32 v[4:5], v[40:41], v[8:9] op_sel_hi:[0,1]
	v_pk_mul_f32 v[4:5], v[4:5], v[6:7]
	v_pk_mul_f32 v[8:9], v[40:41], v[24:25] op_sel_hi:[0,1]
	v_cvt_pk_bf16_f32 v143, v4, v5
	v_pk_mul_f32 v[4:5], v[40:41], v[22:23] op_sel_hi:[0,1]
	v_pk_mul_f32 v[0:1], v[4:5], v[0:1]
	s_nop 0
	v_cvt_pk_bf16_f32 v144, v0, v1
	v_pk_mul_f32 v[0:1], v[40:41], v[10:11] op_sel_hi:[0,1]
	v_pk_mul_f32 v[0:1], v[0:1], v[2:3]
	s_nop 0
	v_cvt_pk_bf16_f32 v145, v0, v1
	global_load_dwordx4 v[0:3], v[174:175], off offset:144
	global_load_dwordx4 v[4:7], v[174:175], off offset:128
	s_waitcnt vmcnt(0)
	v_pk_mul_f32 v[4:5], v[8:9], v[4:5]
	s_nop 0
	v_cvt_pk_bf16_f32 v134, v4, v5
	v_pk_mul_f32 v[4:5], v[40:41], v[26:27] op_sel_hi:[0,1]
	v_pk_mul_f32 v[4:5], v[4:5], v[6:7]
	v_pk_mul_f32 v[8:9], v[40:41], v[32:33] op_sel_hi:[0,1]
	v_cvt_pk_bf16_f32 v135, v4, v5
	v_pk_mul_f32 v[4:5], v[40:41], v[28:29] op_sel_hi:[0,1]
	v_pk_mul_f32 v[0:1], v[4:5], v[0:1]
	s_nop 0
	v_cvt_pk_bf16_f32 v136, v0, v1
	v_pk_mul_f32 v[0:1], v[40:41], v[30:31] op_sel_hi:[0,1]
	v_pk_mul_f32 v[0:1], v[0:1], v[2:3]
	s_nop 0
	v_cvt_pk_bf16_f32 v137, v0, v1
	global_load_dwordx4 v[0:3], v[174:175], off offset:208
	global_load_dwordx4 v[4:7], v[174:175], off offset:192
	global_load_dword v228, v161, s[90:91]
	v_readlane_b32 s90, v255, 3
	v_readlane_b32 s91, v255, 4
	s_waitcnt vmcnt(1)
; #define LAS __attribute__((address_space(3)))
; __device__ __forceinline__ int crow(int r, int h) { return (r & 3) + 8 * (r >> 2) + 4 * h; }
; __device__ __forceinline__ void attn_phase(CArgs a, int l, LAS unsigned char* lds, int tid, int lane, int wave, int G, int bx) {
;     ...
;                 for (int t3 = 0; t3 < 1; ++t3) { const int tt = ps + t3; f32x16 sa;
; #pragma unroll
;                     for (int i = 0; i < 16; ++i) sa[i] = 0.f;
; #pragma unroll
;                     for (int st = 0; st < 4; ++st) { const bf16x8 kf = *(const LAS bf16x8*)(Ks + (kvh * 192 + tt * 32 + ql) * 72 + st * 16 + hf * 8);
;                         sa = __builtin_amdgcn_mfma_f32_32x32x16_bf16(kf, qf[st], sa, 0, 0, 0); }
; #pragma unroll
;                     for (int i = 0; i < 16; ++i) sv[t3][i] = sa[i]; }
;                 float mn = mx;
; #pragma unroll
;                 for (int t3 = 0; t3 < 1; ++t3)
; #pragma unroll
;                     for (int i = 0; i < 16; ++i) { const int s = (ps + t3) * 32 + crow(i, hf); float v = sv[t3][i] + blh[s]; if (s < nmask) v = -1e30f; sv[t3][i] = v; mn = fmaxf(mn, v); }
;                 mn = fmaxf(mn, __shfl_xor(mn, 32));
;                 const float resc = __expf(mx - mn); mx = mn;
;                 float psum = 0.f;
; #pragma unroll
;                 for (int t3 = 0; t3 < 1; ++t3)
; #pragma unroll
;                     for (int i = 0; i < 16; ++i) { const float p = __expf(sv[t3][i] - mx); sv[t3][i] = p; psum += p; }
	v_pk_mul_f32 v[4:5], v[8:9], v[4:5]
	s_nop 0
	v_cvt_pk_bf16_f32 v130, v4, v5
	v_pk_mul_f32 v[4:5], v[40:41], v[34:35] op_sel_hi:[0,1]
	v_pk_mul_f32 v[4:5], v[4:5], v[6:7]
	s_nop 0
	v_cvt_pk_bf16_f32 v131, v4, v5
	v_pk_mul_f32 v[4:5], v[40:41], v[36:37] op_sel_hi:[0,1]
	v_pk_mul_f32 v[0:1], v[4:5], v[0:1]
	s_nop 0
	v_cvt_pk_bf16_f32 v132, v0, v1
	v_pk_mul_f32 v[0:1], v[40:41], v[38:39] op_sel_hi:[0,1]
	v_pk_mul_f32 v[0:1], v[0:1], v[2:3]
	s_nop 0
	v_cvt_pk_bf16_f32 v133, v0, v1
	ds_read_b128 v[0:3], v213
	ds_read_b128 v[16:19], v213 offset:32
	ds_read_b128 v[92:95], v213 offset:64
	ds_read_b128 v[96:99], v213 offset:96
	ds_read2_b32 v[74:75], v229 offset0:63 offset1:64
	ds_read2_b32 v[76:77], v229 offset0:65 offset1:66
	ds_read2_b32 v[78:79], v229 offset0:71 offset1:72
	ds_read2_b32 v[80:81], v229 offset0:73 offset1:74
	ds_read2_b32 v[82:83], v229 offset0:79 offset1:80
	ds_read2_b32 v[84:85], v229 offset0:81 offset1:82
	ds_read2_b32 v[86:87], v229 offset0:87 offset1:88
	ds_read2_b32 v[88:89], v229 offset0:89 offset1:90
	s_waitcnt lgkmcnt(11)
	v_mfma_f32_32x32x16_bf16 v[0:15], v[0:3], v[138:141], 0
	s_waitcnt lgkmcnt(10)
	v_mfma_f32_32x32x16_bf16 v[0:15], v[16:19], v[142:145], v[0:15]
	s_waitcnt lgkmcnt(9)
	v_mfma_f32_32x32x16_bf16 v[0:15], v[92:95], v[134:137], v[0:15]
	s_waitcnt lgkmcnt(8)
	v_mfma_f32_32x32x16_bf16 v[0:15], v[96:99], v[130:133], v[0:15]
	s_waitcnt lgkmcnt(0)
	s_nop 10
	v_add_f32_e32 v0, v0, v74
	v_cndmask_b32_e64 v16, v0, v218, s[90:91]
	v_readlane_b32 s90, v254, 53
	v_add_f32_e32 v0, v1, v75
	v_readlane_b32 s91, v254, 54
	s_nop 1
	v_cndmask_b32_e64 v17, v0, v218, s[90:91]
	v_readlane_b32 s90, v254, 55
	v_readlane_b32 s91, v254, 56
	s_waitcnt vmcnt(0)
	v_max3_f32 v18, v228, v16, v17
	s_waitcnt lgkmcnt(0)
	v_add_f32_e32 v0, v2, v76
	v_cndmask_b32_e64 v2, v0, v218, s[90:91]
	v_readlane_b32 s90, v254, 57
	v_add_f32_e32 v0, v3, v77
	v_readlane_b32 s91, v254, 58
	s_nop 1
	v_cndmask_b32_e64 v3, v0, v218, s[90:91]
	v_readlane_b32 s90, v254, 61
	v_readlane_b32 s91, v254, 62
	v_max3_f32 v18, v18, v2, v3
	s_waitcnt lgkmcnt(0)
	v_add_f32_e32 v0, v4, v78
	v_cndmask_b32_e64 v4, v0, v218, s[90:91]
	v_readlane_b32 s90, v255, 7
	v_add_f32_e32 v0, v5, v79
	v_readlane_b32 s91, v255, 8
	s_nop 1
	v_cndmask_b32_e64 v5, v0, v218, s[90:91]
	v_readlane_b32 s90, v255, 5
	v_readlane_b32 s91, v255, 6
	v_max3_f32 v18, v18, v4, v5
	s_waitcnt lgkmcnt(0)
	v_add_f32_e32 v0, v6, v80
	v_cndmask_b32_e64 v6, v0, v218, s[90:91]
	v_readlane_b32 s90, v255, 9
	v_add_f32_e32 v0, v7, v81
	v_readlane_b32 s91, v255, 10
	s_nop 1
	v_cndmask_b32_e64 v7, v0, v218, s[90:91]
	v_readlane_b32 s90, v255, 11
	v_readlane_b32 s91, v255, 12
	v_max3_f32 v18, v18, v6, v7
	s_waitcnt lgkmcnt(0)
	v_add_f32_e32 v0, v8, v82
	v_cndmask_b32_e64 v8, v0, v218, s[90:91]
	v_readlane_b32 s90, v255, 13
	v_add_f32_e32 v0, v9, v83
	v_readlane_b32 s91, v255, 14
	s_nop 1
	v_cndmask_b32_e64 v9, v0, v218, s[90:91]
	v_readlane_b32 s90, v255, 17
	v_readlane_b32 s91, v255, 18
	v_max3_f32 v18, v18, v8, v9
	s_waitcnt lgkmcnt(0)
	v_add_f32_e32 v0, v10, v84
	v_cndmask_b32_e64 v10, v0, v218, s[90:91]
	v_readlane_b32 s90, v255, 15
	v_add_f32_e32 v0, v11, v85
	v_readlane_b32 s91, v255, 16
	s_nop 1
	v_cndmask_b32_e64 v11, v0, v218, s[90:91]
	v_readlane_b32 s90, v255, 21
	v_readlane_b32 s91, v255, 22
	v_max3_f32 v18, v18, v10, v11
	s_waitcnt lgkmcnt(0)
	v_add_f32_e32 v0, v12, v86
	v_cndmask_b32_e64 v12, v0, v218, s[90:91]
	v_readlane_b32 s90, v255, 19
	v_add_f32_e32 v0, v13, v87
	v_readlane_b32 s91, v255, 20
	s_nop 1
	v_cndmask_b32_e64 v13, v0, v218, s[90:91]
	v_readlane_b32 s90, v255, 23
	v_readlane_b32 s91, v255, 24
	v_max3_f32 v18, v18, v12, v13
	ds_read2_b64 v[34:37], v153 offset1:2
	ds_read2_b64 v[194:197], v153 offset0:4 offset1:6
	s_waitcnt lgkmcnt(2)
	v_add_f32_e32 v0, v14, v88
	v_cndmask_b32_e64 v0, v0, v218, s[90:91]
	v_readlane_b32 s90, v254, 63
	v_add_f32_e32 v1, v15, v89
	v_readlane_b32 s91, v255, 0
	ds_read2_b64 v[198:201], v230 offset0:64 offset1:66
	ds_read2_b64 v[202:205], v230 offset0:68 offset1:70
	v_cndmask_b32_e64 v1, v1, v218, s[90:91]
	v_max3_f32 v14, v18, v0, v1
	ds_bpermute_b32 v15, v171, v14
	v_readlane_b32 s90, v255, 1
	v_readlane_b32 s91, v255, 2
	s_waitcnt lgkmcnt(0)
	v_max_f32_e32 v15, v15, v15
	v_max_f32_e32 v51, v14, v15
	v_sub_f32_e32 v2, v2, v51
	v_mul_f32_e32 v2, 0x3fb8aa3b, v2
	v_exp_f32_e32 v50, v2
	v_sub_f32_e32 v2, v3, v51
	v_mul_f32_e32 v2, 0x3fb8aa3b, v2
	v_exp_f32_e32 v52, v2
	v_sub_f32_e32 v2, v4, v51
	v_mul_f32_e32 v2, 0x3fb8aa3b, v2
	v_exp_f32_e32 v54, v2
	v_sub_f32_e32 v2, v5, v51
	v_mul_f32_e32 v2, 0x3fb8aa3b, v2
	v_exp_f32_e32 v56, v2
	v_sub_f32_e32 v2, v6, v51
	v_mul_f32_e32 v2, 0x3fb8aa3b, v2
	v_exp_f32_e32 v58, v2
	v_sub_f32_e32 v2, v7, v51
	v_mul_f32_e32 v2, 0x3fb8aa3b, v2
	v_exp_f32_e32 v60, v2
	v_sub_f32_e32 v2, v8, v51
	v_mul_f32_e32 v2, 0x3fb8aa3b, v2
	v_exp_f32_e32 v62, v2
	v_sub_f32_e32 v2, v9, v51
	v_mul_f32_e32 v2, 0x3fb8aa3b, v2
	v_sub_f32_e32 v0, v0, v51
	v_sub_f32_e32 v15, v16, v51
	v_exp_f32_e32 v64, v2
	v_sub_f32_e32 v2, v10, v51
	v_mul_f32_e32 v0, 0x3fb8aa3b, v0
	v_sub_f32_e32 v14, v228, v51
	v_mul_f32_e32 v15, 0x3fb8aa3b, v15
	v_mul_f32_e32 v2, 0x3fb8aa3b, v2
	v_exp_f32_e32 v186, v0
	v_sub_f32_e32 v0, v1, v51
	v_mul_f32_e32 v14, 0x3fb8aa3b, v14
	v_exp_f32_e32 v16, v15
	v_sub_f32_e32 v15, v17, v51
	v_exp_f32_e32 v178, v2
	v_sub_f32_e32 v2, v11, v51
	v_mul_f32_e32 v0, 0x3fb8aa3b, v0
	v_mul_f32_e32 v15, 0x3fb8aa3b, v15
	v_mul_f32_e32 v2, 0x3fb8aa3b, v2
	v_exp_f32_e32 v188, v0
	v_exp_f32_e32 v0, v14
	v_exp_f32_e32 v17, v15
	v_exp_f32_e32 v180, v2
	v_sub_f32_e32 v2, v12, v51
	v_mul_f32_e32 v2, 0x3fb8aa3b, v2
	v_exp_f32_e32 v182, v2
; #define LAS __attribute__((address_space(3)))
; __device__ __forceinline__ void attn_phase(CArgs a, int l, LAS unsigned char* lds, int tid, int lane, int wave, int G, int bx) {
;     ...
;                     for (int st = 0; st < 4; ++st) { const bf16x8 kf = *(const LAS bf16x8*)(Ks + (kvh * 192 + tt * 32 + ql) * 72 + st * 16 + hf * 8);
;                         sa = __builtin_amdgcn_mfma_f32_32x32x16_bf16(kf, qf[st], sa, 0, 0, 0); }
; #pragma unroll
;                     for (int i = 0; i < 16; ++i) sv[t3][i] = sa[i]; }
;                 float mn = mx;
; #pragma unroll
;                 for (int t3 = 0; t3 < 1; ++t3)
; #pragma unroll
;                     for (int i = 0; i < 16; ++i) { const int s = (ps + t3) * 32 + crow(i, hf); float v = sv[t3][i] + blh[s]; if (s < nmask) v = -1e30f; sv[t3][i] = v; mn = fmaxf(mn, v); }
;                 mn = fmaxf(mn, __shfl_xor(mn, 32));
;                 const float resc = __expf(mx - mn); mx = mn;
;                 float psum = 0.f;
; #pragma unroll
;                 for (int t3 = 0; t3 < 1; ++t3)
; #pragma unroll
;                     for (int i = 0; i < 16; ++i) { const float p = __expf(sv[t3][i] - mx); sv[t3][i] = p; psum += p; }
;                 sum = sum * resc + psum;
;                 o0 = o0 * resc; o1 = o1 * resc;
; #pragma unroll
;                 for (int t3 = 0; t3 < 1; ++t3)
; #pragma unroll
;                     for (int bb = 0; bb < 2; ++bb) { const int tt = ps + t3;
;                         u32x4 pw; pw.x = pk2(sv[t3][8 * bb], sv[t3][8 * bb + 1]); pw.y = pk2(sv[t3][8 * bb + 2], sv[t3][8 * bb + 3]); pw.z = pk2(sv[t3][8 * bb + 4], sv[t3][8 * bb + 5]); pw.w = pk2(sv[t3][8 * bb + 6], sv[t3][8 * bb + 7]);
;                         const bf16x8 pf = __builtin_bit_cast(bf16x8, pw);
;                         const LAS bf16_t* v0p = Vt + (kvh * 64 + ql) * 200 + tt * 32 + 16 * bb + 4 * hf;
;                         const LAS bf16_t* v1p = v0p + 32 * 200;
;                         u32x4 a0, a1; { const u32x2 lo = *(const LAS u32x2*)v0p, hi = *(const LAS u32x2*)(v0p + 8); a0.x = lo.x; a0.y = lo.y; a0.z = hi.x; a0.w = hi.y; }
;                         { const u32x2 lo = *(const LAS u32x2*)v1p, hi = *(const LAS u32x2*)(v1p + 8); a1.x = lo.x; a1.y = lo.y; a1.z = hi.x; a1.w = hi.y; }
;                         o0 = __builtin_amdgcn_mfma_f32_32x32x16_bf16(__builtin_bit_cast(bf16x8, a0), pf, o0, 0, 0, 0);
	v_sub_f32_e32 v2, v13, v51
	v_mul_f32_e32 v2, 0x3fb8aa3b, v2
	v_mul_f32_e32 v0, 0, v0
	v_exp_f32_e32 v184, v2
	v_mov_b32_e32 v1, v0
	v_mov_b32_e32 v2, v0
	v_mov_b32_e32 v3, v0
	v_mov_b32_e32 v4, v0
	v_mov_b32_e32 v5, v0
	v_mov_b32_e32 v6, v0
	v_mov_b32_e32 v7, v0
	v_mov_b32_e32 v8, v0
	v_mov_b32_e32 v9, v0
	v_mov_b32_e32 v10, v0
	v_mov_b32_e32 v11, v0
	v_mov_b32_e32 v12, v0
	v_mov_b32_e32 v13, v0
	v_mov_b32_e32 v14, v0
	v_mov_b32_e32 v15, v0
	v_cvt_pk_bf16_f32 v190, v16, v17
	v_cvt_pk_bf16_f32 v191, v50, v52
	v_cvt_pk_bf16_f32 v192, v54, v56
	v_cvt_pk_bf16_f32 v193, v58, v60
	s_nop 1
	v_mfma_f32_32x32x16_bf16 v[18:33], v[34:37], v[190:193], v[0:15]
	v_mov_b64_e32 v[48:49], v[14:15]
	v_mov_b64_e32 v[46:47], v[12:13]
	v_mov_b64_e32 v[44:45], v[10:11]
	v_mov_b64_e32 v[42:43], v[8:9]
	v_mov_b64_e32 v[40:41], v[6:7]
	v_mov_b64_e32 v[38:39], v[4:5]
	v_mov_b64_e32 v[36:37], v[2:3]
	v_mov_b64_e32 v[34:35], v[0:1]
	v_cvt_pk_bf16_f32 v2, v62, v64
	v_cvt_pk_bf16_f32 v3, v178, v180
	v_mfma_f32_32x32x16_bf16 v[34:49], v[198:201], v[190:193], v[34:49]
	v_cvt_pk_bf16_f32 v4, v182, v184
	v_cvt_pk_bf16_f32 v5, v186, v188
	v_add_f32_e32 v1, 0, v16
	v_add_f32_e32 v160, v17, v1
	v_mfma_f32_32x32x16_bf16 v[18:33], v[194:197], v[2:5], v[18:33]
	v_mfma_f32_32x32x16_bf16 v[34:49], v[202:205], v[2:5], v[34:49]
	ds_read_b128 v[2:5], v213 offset:4608
	ds_read_b128 v[190:193], v213 offset:4640
	ds_read_b128 v[92:95], v213 offset:4672
	ds_read_b128 v[96:99], v213 offset:4704
	ds_read2_b32 v[100:101], v229 offset0:95 offset1:96
	ds_read2_b32 v[102:103], v229 offset0:97 offset1:98
	ds_read2_b32 v[104:105], v229 offset0:103 offset1:104
	ds_read2_b32 v[106:107], v229 offset0:105 offset1:106
	ds_read2_b32 v[108:109], v229 offset0:111 offset1:112
	ds_read2_b32 v[110:111], v229 offset0:113 offset1:114
	ds_read2_b32 v[112:113], v229 offset0:119 offset1:120
	ds_read2_b32 v[90:91], v229 offset0:121 offset1:122
	s_waitcnt lgkmcnt(11)
	v_mfma_f32_32x32x16_bf16 v[2:17], v[2:5], v[138:141], 0
	s_waitcnt lgkmcnt(10)
	v_mfma_f32_32x32x16_bf16 v[2:17], v[190:193], v[142:145], v[2:17]
	s_waitcnt lgkmcnt(9)
	v_mfma_f32_32x32x16_bf16 v[2:17], v[92:95], v[134:137], v[2:17]
	s_waitcnt lgkmcnt(8)
	v_mfma_f32_32x32x16_bf16 v[2:17], v[96:99], v[130:133], v[2:17]
	s_waitcnt lgkmcnt(0)
	s_nop 10
	v_add_f32_e32 v1, v2, v100
	v_cndmask_b32_e64 v1, v1, v218, s[90:91]
	v_readlane_b32 s90, v254, 59
	v_add_f32_e32 v2, v3, v101
	v_readlane_b32 s91, v254, 60
	s_nop 1
	v_cndmask_b32_e64 v53, v2, v218, s[90:91]
	v_readlane_b32 s90, v254, 51
	v_readlane_b32 s91, v254, 52
	v_max3_f32 v55, v51, v1, v53
	s_waitcnt lgkmcnt(0)
	v_add_f32_e32 v2, v4, v102
	v_cndmask_b32_e64 v4, v2, v218, s[90:91]
	v_readlane_b32 s90, v255, 49
	v_add_f32_e32 v2, v5, v103
	v_readlane_b32 s91, v255, 50
	s_nop 1
	v_cndmask_b32_e64 v5, v2, v218, s[90:91]
	v_max3_f32 v55, v55, v4, v5
	s_waitcnt lgkmcnt(0)
	v_add_f32_e32 v2, v6, v104
	v_cndmask_b32_e64 v6, v2, v218, s[92:93]
	v_add_f32_e32 v2, v7, v105
	v_cndmask_b32_e64 v7, v2, v218, s[94:95]
	v_max3_f32 v55, v55, v6, v7
	s_waitcnt lgkmcnt(0)
	v_add_f32_e32 v2, v8, v106
	v_cndmask_b32_e64 v8, v2, v218, s[96:97]
	v_add_f32_e32 v2, v9, v107
	v_cndmask_b32_e64 v9, v2, v218, s[84:85]
	v_max3_f32 v55, v55, v8, v9
	s_waitcnt lgkmcnt(0)
	v_add_f32_e32 v2, v10, v108
	v_cndmask_b32_e64 v10, v2, v218, s[4:5]
	v_add_f32_e32 v2, v11, v109
	v_cndmask_b32_e64 v11, v2, v218, s[6:7]
	v_max3_f32 v55, v55, v10, v11
	s_waitcnt lgkmcnt(0)
	v_add_f32_e32 v2, v12, v110
	v_cndmask_b32_e64 v12, v2, v218, s[8:9]
	v_add_f32_e32 v2, v13, v111
	v_cndmask_b32_e64 v13, v2, v218, s[10:11]
	v_max3_f32 v55, v55, v12, v13
	s_waitcnt lgkmcnt(0)
	v_add_f32_e32 v2, v14, v112
	v_cndmask_b32_e64 v14, v2, v218, s[12:13]
	v_add_f32_e32 v2, v15, v113
	v_cndmask_b32_e64 v15, v2, v218, s[14:15]
	v_max3_f32 v55, v55, v14, v15
	s_waitcnt lgkmcnt(0)
	v_add_f32_e32 v2, v16, v90
	v_add_f32_e32 v3, v17, v91
	v_cndmask_b32_e64 v2, v2, v218, s[16:17]
	v_cndmask_b32_e64 v3, v3, v218, s[18:19]
	v_max3_f32 v16, v55, v2, v3
	ds_bpermute_b32 v17, v171, v16
	s_waitcnt lgkmcnt(0)
	v_max_f32_e32 v17, v17, v17
	v_max_f32_e32 v191, v16, v17
	v_sub_f32_e32 v1, v1, v191
	v_mul_f32_e32 v1, 0x3fb8aa3b, v1
	v_sub_f32_e32 v16, v51, v191
	v_exp_f32_e32 v51, v1
	v_sub_f32_e32 v1, v53, v191
	v_mul_f32_e32 v1, 0x3fb8aa3b, v1
	v_exp_f32_e32 v53, v1
	v_sub_f32_e32 v1, v4, v191
	v_mul_f32_e32 v1, 0x3fb8aa3b, v1
	v_exp_f32_e32 v55, v1
	v_sub_f32_e32 v1, v5, v191
	v_mul_f32_e32 v1, 0x3fb8aa3b, v1
	v_exp_f32_e32 v57, v1
	v_sub_f32_e32 v1, v6, v191
	v_mul_f32_e32 v1, 0x3fb8aa3b, v1
	v_exp_f32_e32 v59, v1
	v_sub_f32_e32 v1, v7, v191
	v_mul_f32_e32 v1, 0x3fb8aa3b, v1
	v_exp_f32_e32 v61, v1
	v_sub_f32_e32 v1, v8, v191
	v_mul_f32_e32 v1, 0x3fb8aa3b, v1
	v_exp_f32_e32 v63, v1
	v_sub_f32_e32 v1, v9, v191
	v_mul_f32_e32 v1, 0x3fb8aa3b, v1
	v_exp_f32_e32 v65, v1
	v_sub_f32_e32 v1, v10, v191
	v_mul_f32_e32 v1, 0x3fb8aa3b, v1
	v_exp_f32_e32 v179, v1
	v_sub_f32_e32 v1, v11, v191
	v_mul_f32_e32 v1, 0x3fb8aa3b, v1
	v_exp_f32_e32 v181, v1
	v_sub_f32_e32 v1, v12, v191
	v_mul_f32_e32 v1, 0x3fb8aa3b, v1
	v_mul_f32_e32 v16, 0x3fb8aa3b, v16
	v_exp_f32_e32 v183, v1
	v_sub_f32_e32 v1, v13, v191
	v_mul_f32_e32 v1, 0x3fb8aa3b, v1
	v_exp_f32_e32 v190, v16
	v_exp_f32_e32 v185, v1
	v_sub_f32_e32 v1, v14, v191
	v_mul_f32_e32 v1, 0x3fb8aa3b, v1
	v_exp_f32_e32 v187, v1
	v_sub_f32_e32 v1, v15, v191
	v_mul_f32_e32 v1, 0x3fb8aa3b, v1
	v_pk_mul_f32 v[16:17], v[32:33], v[190:191] op_sel_hi:[1,0]
	v_pk_mul_f32 v[14:15], v[30:31], v[190:191] op_sel_hi:[1,0]
	v_pk_mul_f32 v[12:13], v[28:29], v[190:191] op_sel_hi:[1,0]
	v_pk_mul_f32 v[10:11], v[26:27], v[190:191] op_sel_hi:[1,0]
	v_pk_mul_f32 v[8:9], v[24:25], v[190:191] op_sel_hi:[1,0]
	v_pk_mul_f32 v[6:7], v[22:23], v[190:191] op_sel_hi:[1,0]
	v_pk_mul_f32 v[32:33], v[48:49], v[190:191] op_sel_hi:[1,0]
	v_pk_mul_f32 v[30:31], v[46:47], v[190:191] op_sel_hi:[1,0]
	v_pk_mul_f32 v[28:29], v[44:45], v[190:191] op_sel_hi:[1,0]
	v_pk_mul_f32 v[26:27], v[42:43], v[190:191] op_sel_hi:[1,0]
	v_pk_mul_f32 v[24:25], v[40:41], v[190:191] op_sel_hi:[1,0]
	v_pk_mul_f32 v[22:23], v[38:39], v[190:191] op_sel_hi:[1,0]
	ds_read2_b64 v[38:41], v153 offset0:8 offset1:10
	ds_read2_b64 v[42:45], v153 offset0:12 offset1:14
	ds_read2_b64 v[46:49], v230 offset0:72 offset1:74
	ds_read2_b64 v[192:195], v230 offset0:76 offset1:78
	v_exp_f32_e32 v189, v1
	v_sub_f32_e32 v1, v2, v191
	v_sub_f32_e32 v2, v3, v191
	v_mul_f32_e32 v2, 0x3fb8aa3b, v2
	v_exp_f32_e32 v196, v2
	v_pk_mul_f32 v[4:5], v[20:21], v[190:191] op_sel_hi:[1,0]
	v_pk_mul_f32 v[2:3], v[18:19], v[190:191] op_sel_hi:[1,0]
	v_pk_mul_f32 v[20:21], v[36:37], v[190:191] op_sel_hi:[1,0]
	v_pk_mul_f32 v[18:19], v[34:35], v[190:191] op_sel_hi:[1,0]
	v_cvt_pk_bf16_f32 v34, v51, v53
	v_cvt_pk_bf16_f32 v35, v55, v57
	v_cvt_pk_bf16_f32 v36, v59, v61
	v_cvt_pk_bf16_f32 v37, v63, v65
	v_mul_f32_e32 v1, 0x3fb8aa3b, v1
	v_exp_f32_e32 v1, v1
	s_waitcnt lgkmcnt(3)
; #define LAS __attribute__((address_space(3)))
; __device__ __forceinline__ void attn_phase(CArgs a, int l, LAS unsigned char* lds, int tid, int lane, int wave, int G, int bx) {
;     ...
;                     for (int st = 0; st < 4; ++st) { const bf16x8 kf = *(const LAS bf16x8*)(Ks + (kvh * 192 + tt * 32 + ql) * 72 + st * 16 + hf * 8);
;                         sa = __builtin_amdgcn_mfma_f32_32x32x16_bf16(kf, qf[st], sa, 0, 0, 0); }
; #pragma unroll
;                     for (int i = 0; i < 16; ++i) sv[t3][i] = sa[i]; }
;                 float mn = mx;
; #pragma unroll
;                 for (int t3 = 0; t3 < 1; ++t3)
; #pragma unroll
;                     for (int i = 0; i < 16; ++i) { const int s = (ps + t3) * 32 + crow(i, hf); float v = sv[t3][i] + blh[s]; if (s < nmask) v = -1e30f; sv[t3][i] = v; mn = fmaxf(mn, v); }
;                 mn = fmaxf(mn, __shfl_xor(mn, 32));
;                 const float resc = __expf(mx - mn); mx = mn;
;                 float psum = 0.f;
; #pragma unroll
;                 for (int t3 = 0; t3 < 1; ++t3)
; #pragma unroll
;                     for (int i = 0; i < 16; ++i) { const float p = __expf(sv[t3][i] - mx); sv[t3][i] = p; psum += p; }
;                 sum = sum * resc + psum;
;                 o0 = o0 * resc; o1 = o1 * resc;
; #pragma unroll
;                 for (int t3 = 0; t3 < 1; ++t3)
; #pragma unroll
;                     for (int bb = 0; bb < 2; ++bb) { const int tt = ps + t3;
;                         u32x4 pw; pw.x = pk2(sv[t3][8 * bb], sv[t3][8 * bb + 1]); pw.y = pk2(sv[t3][8 * bb + 2], sv[t3][8 * bb + 3]); pw.z = pk2(sv[t3][8 * bb + 4], sv[t3][8 * bb + 5]); pw.w = pk2(sv[t3][8 * bb + 6], sv[t3][8 * bb + 7]);
;                         const bf16x8 pf = __builtin_bit_cast(bf16x8, pw);
;                         const LAS bf16_t* v0p = Vt + (kvh * 64 + ql) * 200 + tt * 32 + 16 * bb + 4 * hf;
;                         const LAS bf16_t* v1p = v0p + 32 * 200;
;                         u32x4 a0, a1; { const u32x2 lo = *(const LAS u32x2*)v0p, hi = *(const LAS u32x2*)(v0p + 8); a0.x = lo.x; a0.y = lo.y; a0.z = hi.x; a0.w = hi.y; }
;                         { const u32x2 lo = *(const LAS u32x2*)v1p, hi = *(const LAS u32x2*)(v1p + 8); a1.x = lo.x; a1.y = lo.y; a1.z = hi.x; a1.w = hi.y; }
;                         o0 = __builtin_amdgcn_mfma_f32_32x32x16_bf16(__builtin_bit_cast(bf16x8, a0), pf, o0, 0, 0, 0);
	v_mfma_f32_32x32x16_bf16 v[2:17], v[38:41], v[34:37], v[2:17]
	s_waitcnt lgkmcnt(1)
	v_mfma_f32_32x32x16_bf16 v[18:33], v[46:49], v[34:37], v[18:33]
	v_cvt_pk_bf16_f32 v34, v179, v181
	v_cvt_pk_bf16_f32 v35, v183, v185
	v_cvt_pk_bf16_f32 v36, v187, v189
	v_cvt_pk_bf16_f32 v37, v1, v196
	s_nop 1
	v_mfma_f32_32x32x16_bf16 v[2:17], v[42:45], v[34:37], v[2:17]
	s_waitcnt lgkmcnt(0)
	v_mfma_f32_32x32x16_bf16 v[18:33], v[192:195], v[34:37], v[18:33]
	v_add_f32_e64 v34, v50, v160
	v_add_f32_e64 v35, v51, v161
	v_add_f32_e64 v34, v52, v34
	v_add_f32_e64 v35, v53, v35
	v_add_f32_e64 v34, v54, v34
	v_add_f32_e64 v35, v55, v35
	v_pk_add_f32 v[34:35], v[56:57], v[34:35]
	s_nop 0
	v_pk_add_f32 v[34:35], v[58:59], v[34:35]
	s_nop 0
	v_pk_add_f32 v[34:35], v[60:61], v[34:35]
	s_nop 0
	v_pk_add_f32 v[34:35], v[62:63], v[34:35]
	s_nop 0
	v_pk_add_f32 v[34:35], v[64:65], v[34:35]
	s_nop 0
	v_pk_add_f32 v[34:35], v[178:179], v[34:35]
	s_nop 0
	v_pk_add_f32 v[34:35], v[180:181], v[34:35]
	s_nop 0
	v_pk_add_f32 v[34:35], v[182:183], v[34:35]
	s_nop 0
	v_pk_add_f32 v[34:35], v[184:185], v[34:35]
	s_nop 0
	v_pk_add_f32 v[34:35], v[186:187], v[34:35]
	s_nop 0
	v_pk_add_f32 v[34:35], v[188:189], v[34:35]
	s_nop 0
	v_pk_add_f32 v[0:1], v[0:1], v[34:35]
	ds_read_b128 v[34:37], v213 offset:9216
	ds_read_b128 v[50:53], v213 offset:9248
	ds_read_b128 v[92:95], v213 offset:9280
	ds_read_b128 v[96:99], v213 offset:9312
	ds_read2_b32 v[74:75], v229 offset0:127 offset1:128
	ds_read2_b32 v[76:77], v229 offset0:129 offset1:130
	ds_read2_b32 v[78:79], v229 offset0:135 offset1:136
	ds_read2_b32 v[80:81], v229 offset0:137 offset1:138
	ds_read2_b32 v[82:83], v229 offset0:143 offset1:144
	ds_read2_b32 v[84:85], v229 offset0:145 offset1:146
	ds_read2_b32 v[86:87], v229 offset0:151 offset1:152
	ds_read2_b32 v[88:89], v229 offset0:153 offset1:154
	s_waitcnt lgkmcnt(11)
	v_mfma_f32_32x32x16_bf16 v[34:49], v[34:37], v[138:141], 0
	v_add_f32_e32 v54, v1, v196
	v_fmac_f32_e32 v54, v0, v190
	s_waitcnt lgkmcnt(10)
	v_mfma_f32_32x32x16_bf16 v[34:49], v[50:53], v[142:145], v[34:49]
	s_waitcnt lgkmcnt(9)
	v_mfma_f32_32x32x16_bf16 v[34:49], v[92:95], v[134:137], v[34:49]
	s_waitcnt lgkmcnt(8)
	v_mfma_f32_32x32x16_bf16 v[34:49], v[96:99], v[130:133], v[34:49]
	s_waitcnt lgkmcnt(0)
	s_nop 10
	v_add_f32_e32 v0, v34, v74
	v_cndmask_b32_e64 v34, v0, v218, s[20:21]
	v_add_f32_e32 v0, v35, v75
	v_cndmask_b32_e64 v35, v0, v218, s[22:23]
	v_max3_f32 v50, v191, v34, v35
	s_waitcnt lgkmcnt(0)
	v_add_f32_e32 v0, v36, v76
	v_cndmask_b32_e64 v36, v0, v218, s[24:25]
	v_add_f32_e32 v0, v37, v77
	v_cndmask_b32_e64 v37, v0, v218, s[26:27]
	v_max3_f32 v50, v50, v36, v37
	s_waitcnt lgkmcnt(0)
	v_add_f32_e32 v0, v38, v78
	v_cndmask_b32_e64 v38, v0, v218, s[28:29]
	v_add_f32_e32 v0, v39, v79
	v_cndmask_b32_e64 v39, v0, v218, s[30:31]
	v_max3_f32 v50, v50, v38, v39
	s_waitcnt lgkmcnt(0)
	v_add_f32_e32 v0, v40, v80
	v_cndmask_b32_e64 v40, v0, v218, s[34:35]
	v_add_f32_e32 v0, v41, v81
	v_cndmask_b32_e64 v41, v0, v218, s[36:37]
	v_max3_f32 v50, v50, v40, v41
	s_waitcnt lgkmcnt(0)
	v_add_f32_e32 v0, v42, v82
	v_cndmask_b32_e64 v42, v0, v218, s[46:47]
	v_add_f32_e32 v0, v43, v83
	v_cndmask_b32_e64 v43, v0, v218, s[0:1]
	v_max3_f32 v50, v50, v42, v43
	s_waitcnt lgkmcnt(0)
	v_add_f32_e32 v0, v44, v84
	v_cndmask_b32_e64 v44, v0, v218, s[48:49]
	v_add_f32_e32 v0, v45, v85
	v_cndmask_b32_e64 v45, v0, v218, s[50:51]
	v_max3_f32 v50, v50, v44, v45
	s_waitcnt lgkmcnt(0)
	v_add_f32_e32 v0, v46, v86
	v_cndmask_b32_e64 v46, v0, v218, s[40:41]
	v_add_f32_e32 v0, v47, v87
	v_cndmask_b32_e64 v47, v0, v218, s[42:43]
	v_max3_f32 v50, v50, v46, v47
	s_waitcnt lgkmcnt(0)
	v_add_f32_e32 v0, v48, v88
	v_add_f32_e32 v1, v49, v89
	v_cndmask_b32_e64 v0, v0, v218, s[44:45]
	v_cndmask_b32_e64 v1, v1, v218, s[38:39]
	v_max3_f32 v48, v50, v0, v1
	ds_bpermute_b32 v49, v171, v48
	s_waitcnt lgkmcnt(0)
	v_max_f32_e32 v49, v49, v49
	v_max_f32_e32 v179, v48, v49
	v_sub_f32_e32 v34, v34, v179
	v_mul_f32_e32 v34, 0x3fb8aa3b, v34
	v_exp_f32_e32 v160, v34
	v_sub_f32_e32 v34, v35, v179
	v_mul_f32_e32 v34, 0x3fb8aa3b, v34
	v_exp_f32_e32 v181, v34
	v_sub_f32_e32 v34, v36, v179
	v_mul_f32_e32 v34, 0x3fb8aa3b, v34
	v_exp_f32_e32 v178, v34
	v_sub_f32_e32 v34, v37, v179
	v_mul_f32_e32 v34, 0x3fb8aa3b, v34
	v_exp_f32_e32 v180, v34
	v_sub_f32_e32 v34, v38, v179
	v_mul_f32_e32 v34, 0x3fb8aa3b, v34
	v_exp_f32_e32 v182, v34
	v_sub_f32_e32 v34, v39, v179
	v_mul_f32_e32 v34, 0x3fb8aa3b, v34
	v_exp_f32_e32 v184, v34
	v_sub_f32_e32 v34, v40, v179
	v_mul_f32_e32 v34, 0x3fb8aa3b, v34
	v_exp_f32_e32 v186, v34
	v_sub_f32_e32 v34, v41, v179
	v_mul_f32_e32 v34, 0x3fb8aa3b, v34
	v_exp_f32_e32 v188, v34
	v_sub_f32_e32 v34, v42, v179
	v_mul_f32_e32 v34, 0x3fb8aa3b, v34
	v_exp_f32_e32 v190, v34
	v_sub_f32_e32 v34, v43, v179
	v_sub_f32_e32 v0, v0, v179
	v_mul_f32_e32 v34, 0x3fb8aa3b, v34
	v_mul_f32_e32 v0, 0x3fb8aa3b, v0
	v_sub_f32_e32 v48, v191, v179
	v_exp_f32_e32 v192, v34
	v_sub_f32_e32 v34, v44, v179
	v_exp_f32_e32 v202, v0
	v_sub_f32_e32 v0, v1, v179
	v_mul_f32_e32 v48, 0x3fb8aa3b, v48
	v_mul_f32_e32 v34, 0x3fb8aa3b, v34
	v_mul_f32_e32 v0, 0x3fb8aa3b, v0
	v_exp_f32_e32 v194, v34
	v_sub_f32_e32 v34, v45, v179
	v_exp_f32_e32 v204, v0
	v_exp_f32_e32 v0, v48
	v_mul_f32_e32 v34, 0x3fb8aa3b, v34
	v_exp_f32_e32 v196, v34
	v_sub_f32_e32 v34, v46, v179
	v_mul_f32_e32 v34, 0x3fb8aa3b, v34
	v_exp_f32_e32 v198, v34
	v_sub_f32_e32 v34, v47, v179
	v_pk_mul_f32 v[48:49], v[16:17], v[0:1] op_sel_hi:[1,0]
	v_pk_mul_f32 v[46:47], v[14:15], v[0:1] op_sel_hi:[1,0]
	v_pk_mul_f32 v[44:45], v[12:13], v[0:1] op_sel_hi:[1,0]
	v_pk_mul_f32 v[42:43], v[10:11], v[0:1] op_sel_hi:[1,0]
	v_pk_mul_f32 v[40:41], v[8:9], v[0:1] op_sel_hi:[1,0]
	v_pk_mul_f32 v[38:39], v[6:7], v[0:1] op_sel_hi:[1,0]
	v_pk_mul_f32 v[36:37], v[4:5], v[0:1] op_sel_hi:[1,0]
	v_pk_mul_f32 v[50:51], v[18:19], v[0:1] op_sel_hi:[1,0]
	ds_read2_b64 v[4:7], v153 offset0:16 offset1:18
	ds_read2_b64 v[8:11], v153 offset0:20 offset1:22
	ds_read2_b64 v[12:15], v230 offset0:80 offset1:82
	ds_read2_b64 v[16:19], v230 offset0:84 offset1:86
	v_mul_f32_e32 v34, 0x3fb8aa3b, v34
	v_exp_f32_e32 v200, v34
	v_mul_f32_e32 v206, v54, v0
	v_pk_mul_f32 v[34:35], v[2:3], v[0:1] op_sel_hi:[1,0]
	v_pk_mul_f32 v[64:65], v[32:33], v[0:1] op_sel_hi:[1,0]
	v_pk_mul_f32 v[62:63], v[30:31], v[0:1] op_sel_hi:[1,0]
	v_pk_mul_f32 v[60:61], v[28:29], v[0:1] op_sel_hi:[1,0]
	v_pk_mul_f32 v[58:59], v[26:27], v[0:1] op_sel_hi:[1,0]
	v_pk_mul_f32 v[56:57], v[24:25], v[0:1] op_sel_hi:[1,0]
	v_pk_mul_f32 v[54:55], v[22:23], v[0:1] op_sel_hi:[1,0]
	v_pk_mul_f32 v[52:53], v[20:21], v[0:1] op_sel_hi:[1,0]
	v_cvt_pk_bf16_f32 v0, v160, v181
	v_cvt_pk_bf16_f32 v1, v178, v180
	v_cvt_pk_bf16_f32 v2, v182, v184
	v_cvt_pk_bf16_f32 v3, v186, v188
	s_waitcnt lgkmcnt(3)
; #define LAS __attribute__((address_space(3)))
; __device__ __forceinline__ void attn_phase(CArgs a, int l, LAS unsigned char* lds, int tid, int lane, int wave, int G, int bx) {
;     ...
;                     for (int st = 0; st < 4; ++st) { const bf16x8 kf = *(const LAS bf16x8*)(Ks + (kvh * 192 + tt * 32 + ql) * 72 + st * 16 + hf * 8);
;                         sa = __builtin_amdgcn_mfma_f32_32x32x16_bf16(kf, qf[st], sa, 0, 0, 0); }
; #pragma unroll
;                     for (int i = 0; i < 16; ++i) sv[t3][i] = sa[i]; }
;                 float mn = mx;
; #pragma unroll
;                 for (int t3 = 0; t3 < 1; ++t3)
; #pragma unroll
;                     for (int i = 0; i < 16; ++i) { const int s = (ps + t3) * 32 + crow(i, hf); float v = sv[t3][i] + blh[s]; if (s < nmask) v = -1e30f; sv[t3][i] = v; mn = fmaxf(mn, v); }
;                 mn = fmaxf(mn, __shfl_xor(mn, 32));
;                 const float resc = __expf(mx - mn); mx = mn;
;                 float psum = 0.f;
; #pragma unroll
;                 for (int t3 = 0; t3 < 1; ++t3)
; #pragma unroll
;                     for (int i = 0; i < 16; ++i) { const float p = __expf(sv[t3][i] - mx); sv[t3][i] = p; psum += p; }
;                 sum = sum * resc + psum;
;                 o0 = o0 * resc; o1 = o1 * resc;
; #pragma unroll
;                 for (int t3 = 0; t3 < 1; ++t3)
; #pragma unroll
;                     for (int bb = 0; bb < 2; ++bb) { const int tt = ps + t3;
;                         u32x4 pw; pw.x = pk2(sv[t3][8 * bb], sv[t3][8 * bb + 1]); pw.y = pk2(sv[t3][8 * bb + 2], sv[t3][8 * bb + 3]); pw.z = pk2(sv[t3][8 * bb + 4], sv[t3][8 * bb + 5]); pw.w = pk2(sv[t3][8 * bb + 6], sv[t3][8 * bb + 7]);
;                         const bf16x8 pf = __builtin_bit_cast(bf16x8, pw);
;                         const LAS bf16_t* v0p = Vt + (kvh * 64 + ql) * 200 + tt * 32 + 16 * bb + 4 * hf;
;                         const LAS bf16_t* v1p = v0p + 32 * 200;
;                         u32x4 a0, a1; { const u32x2 lo = *(const LAS u32x2*)v0p, hi = *(const LAS u32x2*)(v0p + 8); a0.x = lo.x; a0.y = lo.y; a0.z = hi.x; a0.w = hi.y; }
;                         { const u32x2 lo = *(const LAS u32x2*)v1p, hi = *(const LAS u32x2*)(v1p + 8); a1.x = lo.x; a1.y = lo.y; a1.z = hi.x; a1.w = hi.y; }
;                         o0 = __builtin_amdgcn_mfma_f32_32x32x16_bf16(__builtin_bit_cast(bf16x8, a0), pf, o0, 0, 0, 0);
	s_nop 0
	v_mfma_f32_32x32x16_bf16 v[34:49], v[4:7], v[0:3], v[34:49]
	s_waitcnt lgkmcnt(1)
	v_mfma_f32_32x32x16_bf16 v[50:65], v[12:15], v[0:3], v[50:65]
	v_cvt_pk_bf16_f32 v0, v190, v192
	v_cvt_pk_bf16_f32 v1, v194, v196
	v_cvt_pk_bf16_f32 v2, v198, v200
	v_cvt_pk_bf16_f32 v3, v202, v204
	s_nop 1
	v_mfma_f32_32x32x16_bf16 v[34:49], v[8:11], v[0:3], v[34:49]
	s_waitcnt lgkmcnt(0)
	v_mfma_f32_32x32x16_bf16 v[50:65], v[16:19], v[0:3], v[50:65]
	v_add_f32_e32 v0, 0, v160
	v_add_f32_e32 v160, v181, v0
	ds_read_b128 v[0:3], v213 offset:13824
	ds_read_b128 v[16:19], v213 offset:13856
	ds_read_b128 v[92:95], v213 offset:13888
	ds_read_b128 v[96:99], v213 offset:13920
	ds_read2_b32 v[100:101], v229 offset0:159 offset1:160
	ds_read2_b32 v[102:103], v229 offset0:161 offset1:162
	ds_read2_b32 v[104:105], v229 offset0:167 offset1:168
	ds_read2_b32 v[106:107], v229 offset0:169 offset1:170
	ds_read2_b32 v[108:109], v229 offset0:175 offset1:176
	ds_read2_b32 v[110:111], v229 offset0:177 offset1:178
	ds_read2_b32 v[112:113], v229 offset0:183 offset1:184
	ds_read2_b32 v[90:91], v229 offset0:185 offset1:186
	s_waitcnt lgkmcnt(11)
	v_mfma_f32_32x32x16_bf16 v[0:15], v[0:3], v[138:141], 0
	s_waitcnt lgkmcnt(10)
	v_mfma_f32_32x32x16_bf16 v[0:15], v[16:19], v[142:145], v[0:15]
	s_waitcnt lgkmcnt(9)
	v_mfma_f32_32x32x16_bf16 v[0:15], v[92:95], v[134:137], v[0:15]
	s_waitcnt lgkmcnt(8)
	v_mfma_f32_32x32x16_bf16 v[0:15], v[96:99], v[130:133], v[0:15]
	s_waitcnt lgkmcnt(0)
	s_nop 10
	v_add_f32_e32 v0, v0, v100
	v_cndmask_b32_e64 v16, v0, v218, s[52:53]
	v_add_f32_e32 v0, v1, v101
	v_cndmask_b32_e64 v17, v0, v218, s[54:55]
	v_max3_f32 v18, v179, v16, v17
	s_waitcnt lgkmcnt(0)
	v_add_f32_e32 v0, v2, v102
	v_cndmask_b32_e64 v2, v0, v218, s[56:57]
	v_add_f32_e32 v0, v3, v103
	v_cndmask_b32_e64 v3, v0, v218, s[58:59]
	v_max3_f32 v18, v18, v2, v3
	s_waitcnt lgkmcnt(0)
	v_add_f32_e32 v0, v4, v104
	v_cndmask_b32_e64 v4, v0, v218, s[60:61]
	v_add_f32_e32 v0, v5, v105
	v_cndmask_b32_e64 v5, v0, v218, s[62:63]
	v_max3_f32 v18, v18, v4, v5
	s_waitcnt lgkmcnt(0)
	v_add_f32_e32 v0, v6, v106
	v_cndmask_b32_e64 v6, v0, v218, s[64:65]
	v_add_f32_e32 v0, v7, v107
	v_cndmask_b32_e64 v7, v0, v218, s[66:67]
	v_max3_f32 v18, v18, v6, v7
	s_waitcnt lgkmcnt(0)
	v_add_f32_e32 v0, v8, v108
	v_cndmask_b32_e64 v8, v0, v218, s[68:69]
	v_add_f32_e32 v0, v9, v109
	v_cndmask_b32_e64 v9, v0, v218, s[70:71]
	v_max3_f32 v18, v18, v8, v9
	s_waitcnt lgkmcnt(0)
	v_add_f32_e32 v0, v10, v110
	v_cndmask_b32_e64 v10, v0, v218, s[72:73]
	v_add_f32_e32 v0, v11, v111
	v_cndmask_b32_e64 v11, v0, v218, s[74:75]
	v_max3_f32 v18, v18, v10, v11
	s_waitcnt lgkmcnt(0)
	v_add_f32_e32 v0, v12, v112
	v_cndmask_b32_e64 v12, v0, v218, s[76:77]
	v_add_f32_e32 v0, v13, v113
	v_cndmask_b32_e64 v13, v0, v218, s[78:79]
	v_max3_f32 v18, v18, v12, v13
	s_waitcnt lgkmcnt(0)
	v_add_f32_e32 v0, v14, v90
	v_add_f32_e32 v1, v15, v91
	v_cndmask_b32_e64 v0, v0, v218, s[80:81]
	v_cndmask_b32_e64 v1, v1, v218, s[82:83]
	v_max3_f32 v14, v18, v0, v1
	ds_bpermute_b32 v15, v171, v14
	s_waitcnt lgkmcnt(0)
	v_max_f32_e32 v15, v15, v15
	v_max_f32_e32 v231, v14, v15
	v_sub_f32_e32 v2, v2, v231
	v_mul_f32_e32 v2, 0x3fb8aa3b, v2
	v_exp_f32_e32 v183, v2
	v_sub_f32_e32 v2, v3, v231
	v_mul_f32_e32 v2, 0x3fb8aa3b, v2
	v_exp_f32_e32 v185, v2
	v_sub_f32_e32 v2, v4, v231
	v_mul_f32_e32 v2, 0x3fb8aa3b, v2
	v_exp_f32_e32 v187, v2
	v_sub_f32_e32 v2, v5, v231
	v_mul_f32_e32 v2, 0x3fb8aa3b, v2
	v_exp_f32_e32 v189, v2
	v_sub_f32_e32 v2, v6, v231
	v_mul_f32_e32 v2, 0x3fb8aa3b, v2
	v_exp_f32_e32 v191, v2
	v_sub_f32_e32 v2, v7, v231
	v_mul_f32_e32 v2, 0x3fb8aa3b, v2
	v_exp_f32_e32 v193, v2
	v_sub_f32_e32 v2, v8, v231
	v_mul_f32_e32 v2, 0x3fb8aa3b, v2
	v_exp_f32_e32 v195, v2
	v_sub_f32_e32 v2, v9, v231
	v_sub_f32_e32 v0, v0, v231
	v_mul_f32_e32 v2, 0x3fb8aa3b, v2
	v_mul_f32_e32 v0, 0x3fb8aa3b, v0
	v_sub_f32_e32 v14, v179, v231
	v_exp_f32_e32 v197, v2
	v_sub_f32_e32 v2, v10, v231
	v_exp_f32_e32 v207, v0
	v_sub_f32_e32 v0, v1, v231
	v_mul_f32_e32 v14, 0x3fb8aa3b, v14
	v_sub_f32_e32 v15, v16, v231
	v_mul_f32_e32 v2, 0x3fb8aa3b, v2
	v_mul_f32_e32 v0, 0x3fb8aa3b, v0
	v_mul_f32_e32 v15, 0x3fb8aa3b, v15
	v_exp_f32_e32 v199, v2
	v_sub_f32_e32 v2, v11, v231
	v_exp_f32_e32 v33, v0
	v_exp_f32_e32 v32, v14
	v_exp_f32_e32 v179, v15
	v_sub_f32_e32 v15, v17, v231
	v_mul_f32_e32 v2, 0x3fb8aa3b, v2
	v_mul_f32_e32 v15, 0x3fb8aa3b, v15
	v_exp_f32_e32 v201, v2
	v_sub_f32_e32 v2, v12, v231
	v_exp_f32_e32 v181, v15
	v_mul_f32_e32 v2, 0x3fb8aa3b, v2
	v_exp_f32_e32 v203, v2
	v_sub_f32_e32 v2, v13, v231
	v_pk_mul_f32 v[14:15], v[48:49], v[32:33] op_sel_hi:[1,0]
	v_pk_mul_f32 v[12:13], v[46:47], v[32:33] op_sel_hi:[1,0]
	v_pk_mul_f32 v[10:11], v[44:45], v[32:33] op_sel_hi:[1,0]
	v_pk_mul_f32 v[8:9], v[42:43], v[32:33] op_sel_hi:[1,0]
	v_pk_mul_f32 v[6:7], v[40:41], v[32:33] op_sel_hi:[1,0]
	v_pk_mul_f32 v[4:5], v[38:39], v[32:33] op_sel_hi:[1,0]
	v_pk_mul_f32 v[18:19], v[52:53], v[32:33] op_sel_hi:[1,0]
	v_pk_mul_f32 v[16:17], v[50:51], v[32:33] op_sel_hi:[1,0]
	ds_read2_b64 v[38:41], v153 offset0:24 offset1:26
	ds_read2_b64 v[42:45], v153 offset0:28 offset1:30
	ds_read2_b64 v[46:49], v230 offset0:88 offset1:90
	ds_read2_b64 v[50:53], v230 offset0:92 offset1:94
	v_mul_f32_e32 v2, 0x3fb8aa3b, v2
	v_exp_f32_e32 v205, v2
	v_pk_mul_f32 v[2:3], v[36:37], v[32:33] op_sel_hi:[1,0]
	v_pk_mul_f32 v[0:1], v[34:35], v[32:33] op_sel_hi:[1,0]
	v_pk_mul_f32 v[30:31], v[64:65], v[32:33] op_sel_hi:[1,0]
	v_pk_mul_f32 v[28:29], v[62:63], v[32:33] op_sel_hi:[1,0]
	v_pk_mul_f32 v[26:27], v[60:61], v[32:33] op_sel_hi:[1,0]
	v_pk_mul_f32 v[24:25], v[58:59], v[32:33] op_sel_hi:[1,0]
	v_pk_mul_f32 v[22:23], v[56:57], v[32:33] op_sel_hi:[1,0]
	v_pk_mul_f32 v[20:21], v[54:55], v[32:33] op_sel_hi:[1,0]
	v_cvt_pk_bf16_f32 v34, v179, v181
	v_cvt_pk_bf16_f32 v35, v183, v185
	v_cvt_pk_bf16_f32 v36, v187, v189
	v_cvt_pk_bf16_f32 v37, v191, v193
	s_waitcnt lgkmcnt(3)
; #define LAS __attribute__((address_space(3)))
; __device__ __forceinline__ void attn_phase(CArgs a, int l, LAS unsigned char* lds, int tid, int lane, int wave, int G, int bx) {
;     ...
;                     for (int st = 0; st < 4; ++st) { const bf16x8 kf = *(const LAS bf16x8*)(Ks + (kvh * 192 + tt * 32 + ql) * 72 + st * 16 + hf * 8);
;                         sa = __builtin_amdgcn_mfma_f32_32x32x16_bf16(kf, qf[st], sa, 0, 0, 0); }
; #pragma unroll
;                     for (int i = 0; i < 16; ++i) sv[t3][i] = sa[i]; }
;                 float mn = mx;
; #pragma unroll
;                 for (int t3 = 0; t3 < 1; ++t3)
; #pragma unroll
;                     for (int i = 0; i < 16; ++i) { const int s = (ps + t3) * 32 + crow(i, hf); float v = sv[t3][i] + blh[s]; if (s < nmask) v = -1e30f; sv[t3][i] = v; mn = fmaxf(mn, v); }
;                 mn = fmaxf(mn, __shfl_xor(mn, 32));
;                 const float resc = __expf(mx - mn); mx = mn;
;                 float psum = 0.f;
; #pragma unroll
;                 for (int t3 = 0; t3 < 1; ++t3)
; #pragma unroll
;                     for (int i = 0; i < 16; ++i) { const float p = __expf(sv[t3][i] - mx); sv[t3][i] = p; psum += p; }
;                 sum = sum * resc + psum;
;                 o0 = o0 * resc; o1 = o1 * resc;
; #pragma unroll
;                 for (int t3 = 0; t3 < 1; ++t3)
; #pragma unroll
;                     for (int bb = 0; bb < 2; ++bb) { const int tt = ps + t3;
;                         u32x4 pw; pw.x = pk2(sv[t3][8 * bb], sv[t3][8 * bb + 1]); pw.y = pk2(sv[t3][8 * bb + 2], sv[t3][8 * bb + 3]); pw.z = pk2(sv[t3][8 * bb + 4], sv[t3][8 * bb + 5]); pw.w = pk2(sv[t3][8 * bb + 6], sv[t3][8 * bb + 7]);
;                         const bf16x8 pf = __builtin_bit_cast(bf16x8, pw);
;                         const LAS bf16_t* v0p = Vt + (kvh * 64 + ql) * 200 + tt * 32 + 16 * bb + 4 * hf;
;                         const LAS bf16_t* v1p = v0p + 32 * 200;
;                         u32x4 a0, a1; { const u32x2 lo = *(const LAS u32x2*)v0p, hi = *(const LAS u32x2*)(v0p + 8); a0.x = lo.x; a0.y = lo.y; a0.z = hi.x; a0.w = hi.y; }
;                         { const u32x2 lo = *(const LAS u32x2*)v1p, hi = *(const LAS u32x2*)(v1p + 8); a1.x = lo.x; a1.y = lo.y; a1.z = hi.x; a1.w = hi.y; }
;                         o0 = __builtin_amdgcn_mfma_f32_32x32x16_bf16(__builtin_bit_cast(bf16x8, a0), pf, o0, 0, 0, 0);
	s_nop 0
	v_mfma_f32_32x32x16_bf16 v[0:15], v[38:41], v[34:37], v[0:15]
	s_waitcnt lgkmcnt(1)
	v_mfma_f32_32x32x16_bf16 v[16:31], v[46:49], v[34:37], v[16:31]
	v_cvt_pk_bf16_f32 v34, v195, v197
	v_cvt_pk_bf16_f32 v35, v199, v201
	v_cvt_pk_bf16_f32 v36, v203, v205
	v_cvt_pk_bf16_f32 v37, v207, v33
	s_nop 1
	v_mfma_f32_32x32x16_bf16 v[0:15], v[42:45], v[34:37], v[0:15]
	s_waitcnt lgkmcnt(0)
	v_mfma_f32_32x32x16_bf16 v[16:31], v[50:53], v[34:37], v[16:31]
	v_add_f32_e64 v34, v178, v160
	v_add_f32_e64 v35, v179, v161
	v_add_f32_e64 v34, v180, v34
	v_add_f32_e64 v35, v181, v35
	v_add_f32_e64 v34, v182, v34
	v_add_f32_e64 v35, v183, v35
	v_pk_add_f32 v[34:35], v[184:185], v[34:35]
	s_nop 0
	v_pk_add_f32 v[34:35], v[186:187], v[34:35]
	s_nop 0
	v_pk_add_f32 v[34:35], v[188:189], v[34:35]
	s_nop 0
	v_pk_add_f32 v[34:35], v[190:191], v[34:35]
	s_nop 0
	v_pk_add_f32 v[34:35], v[192:193], v[34:35]
	s_nop 0
	v_pk_add_f32 v[34:35], v[194:195], v[34:35]
	s_nop 0
	v_pk_add_f32 v[34:35], v[196:197], v[34:35]
	s_nop 0
	v_pk_add_f32 v[34:35], v[198:199], v[34:35]
	s_nop 0
	v_pk_add_f32 v[34:35], v[200:201], v[34:35]
	s_nop 0
	v_pk_add_f32 v[34:35], v[202:203], v[34:35]
	s_nop 0
	v_pk_add_f32 v[34:35], v[204:205], v[34:35]
	s_nop 0
	v_pk_add_f32 v[34:35], v[206:207], v[34:35]
	s_nop 0
	v_add_f32_e32 v51, v35, v33
	v_fmac_f32_e32 v51, v34, v32
	ds_read_b128 v[32:35], v213 offset:18432
	ds_read_b128 v[52:55], v213 offset:18464
	ds_read_b128 v[92:95], v213 offset:18496
	ds_read_b128 v[96:99], v213 offset:18528
	ds_read2_b32 v[74:75], v229 offset0:191 offset1:192
	ds_read2_b32 v[76:77], v229 offset0:193 offset1:194
	ds_read2_b32 v[78:79], v229 offset0:199 offset1:200
	ds_read2_b32 v[80:81], v229 offset0:201 offset1:202
	ds_read2_b32 v[82:83], v229 offset0:207 offset1:208
	ds_read2_b32 v[84:85], v229 offset0:209 offset1:210
	ds_read2_b32 v[86:87], v229 offset0:215 offset1:216
	ds_read2_b32 v[88:89], v229 offset0:217 offset1:218
	s_waitcnt lgkmcnt(11)
	v_mfma_f32_32x32x16_bf16 v[32:47], v[32:35], v[138:141], 0
	s_waitcnt lgkmcnt(10)
	v_mfma_f32_32x32x16_bf16 v[32:47], v[52:55], v[142:145], v[32:47]
	s_waitcnt lgkmcnt(9)
	v_mfma_f32_32x32x16_bf16 v[32:47], v[92:95], v[134:137], v[32:47]
	s_waitcnt lgkmcnt(8)
	v_mfma_f32_32x32x16_bf16 v[32:47], v[96:99], v[130:133], v[32:47]
	s_waitcnt lgkmcnt(0)
	s_nop 10
	v_add_f32_e32 v48, v32, v74
	v_add_f32_e32 v50, v33, v75
	v_max3_f32 v49, v231, v48, v50
	s_waitcnt lgkmcnt(0)
	v_add_f32_e32 v34, v34, v76
	v_add_f32_e32 v35, v35, v77
	v_max3_f32 v49, v49, v34, v35
	s_waitcnt lgkmcnt(0)
	v_add_f32_e32 v36, v36, v78
	v_add_f32_e32 v37, v37, v79
	v_max3_f32 v49, v49, v36, v37
	s_waitcnt lgkmcnt(0)
	v_add_f32_e32 v38, v38, v80
	v_add_f32_e32 v39, v39, v81
	v_max3_f32 v49, v49, v38, v39
	s_waitcnt lgkmcnt(0)
	v_add_f32_e32 v40, v40, v82
	v_add_f32_e32 v41, v41, v83
	v_max3_f32 v49, v49, v40, v41
	s_waitcnt lgkmcnt(0)
	v_add_f32_e32 v42, v42, v84
	v_add_f32_e32 v43, v43, v85
	v_max3_f32 v49, v49, v42, v43
	s_waitcnt lgkmcnt(0)
	v_add_f32_e32 v44, v44, v86
	v_add_f32_e32 v45, v45, v87
	v_max3_f32 v49, v49, v44, v45
	s_waitcnt lgkmcnt(0)
	v_add_f32_e32 v32, v46, v88
	v_add_f32_e32 v33, v47, v89
	v_max3_f32 v46, v49, v32, v33
	ds_bpermute_b32 v47, v171, v46
	s_waitcnt lgkmcnt(0)
	v_max_f32_e32 v47, v47, v47
	v_max_f32_e32 v49, v46, v47
	v_sub_f32_e32 v34, v34, v49
	v_mul_f32_e32 v34, 0x3fb8aa3b, v34
	v_exp_f32_e32 v186, v34
	v_sub_f32_e32 v34, v35, v49
	v_mul_f32_e32 v34, 0x3fb8aa3b, v34
	v_exp_f32_e32 v184, v34
	v_sub_f32_e32 v34, v36, v49
	v_mul_f32_e32 v34, 0x3fb8aa3b, v34
	v_exp_f32_e32 v182, v34
	v_sub_f32_e32 v34, v37, v49
	v_mul_f32_e32 v34, 0x3fb8aa3b, v34
	v_exp_f32_e32 v180, v34
	v_sub_f32_e32 v34, v38, v49
	v_mul_f32_e32 v34, 0x3fb8aa3b, v34
	v_exp_f32_e32 v178, v34
	v_sub_f32_e32 v34, v39, v49
	v_mul_f32_e32 v34, 0x3fb8aa3b, v34
	v_exp_f32_e32 v64, v34
	v_sub_f32_e32 v34, v40, v49
	v_mul_f32_e32 v34, 0x3fb8aa3b, v34
	v_exp_f32_e32 v62, v34
	v_sub_f32_e32 v34, v41, v49
	v_mul_f32_e32 v34, 0x3fb8aa3b, v34
	v_exp_f32_e32 v60, v34
	v_sub_f32_e32 v34, v42, v49
	v_sub_f32_e32 v47, v48, v49
	v_mul_f32_e32 v34, 0x3fb8aa3b, v34
	v_sub_f32_e32 v32, v32, v49
	v_mul_f32_e32 v47, 0x3fb8aa3b, v47
	v_exp_f32_e32 v58, v34
	v_sub_f32_e32 v34, v43, v49
	v_mul_f32_e32 v32, 0x3fb8aa3b, v32
	v_sub_f32_e32 v46, v231, v49
	v_exp_f32_e32 v53, v47
	v_sub_f32_e32 v47, v50, v49
	v_mul_f32_e32 v34, 0x3fb8aa3b, v34
	v_exp_f32_e32 v50, v32
	v_sub_f32_e32 v32, v33, v49
	v_mul_f32_e32 v46, 0x3fb8aa3b, v46
	v_mul_f32_e32 v47, 0x3fb8aa3b, v47
	v_exp_f32_e32 v56, v34
	v_sub_f32_e32 v34, v44, v49
	v_mul_f32_e32 v32, 0x3fb8aa3b, v32
	v_exp_f32_e32 v55, v47
	v_mul_f32_e32 v34, 0x3fb8aa3b, v34
	v_exp_f32_e32 v48, v32
	v_exp_f32_e32 v32, v46
	v_exp_f32_e32 v54, v34
	v_sub_f32_e32 v34, v45, v49
	ds_read2_b64 v[36:39], v153 offset0:32 offset1:34
	ds_read2_b64 v[40:43], v153 offset0:36 offset1:38
	ds_read2_b64 v[44:47], v230 offset0:96 offset1:98
	ds_read2_b64 v[190:193], v230 offset0:100 offset1:102
	v_mul_f32_e32 v34, 0x3fb8aa3b, v34
	v_exp_f32_e32 v52, v34
	v_mul_f32_e32 v188, v51, v32
	v_pk_mul_f32 v[14:15], v[14:15], v[32:33] op_sel_hi:[1,0]
	v_pk_mul_f32 v[12:13], v[12:13], v[32:33] op_sel_hi:[1,0]
	v_pk_mul_f32 v[10:11], v[10:11], v[32:33] op_sel_hi:[1,0]
	v_pk_mul_f32 v[8:9], v[8:9], v[32:33] op_sel_hi:[1,0]
	v_pk_mul_f32 v[6:7], v[6:7], v[32:33] op_sel_hi:[1,0]
	v_pk_mul_f32 v[4:5], v[4:5], v[32:33] op_sel_hi:[1,0]
	v_pk_mul_f32 v[2:3], v[2:3], v[32:33] op_sel_hi:[1,0]
	v_pk_mul_f32 v[0:1], v[0:1], v[32:33] op_sel_hi:[1,0]
	v_pk_mul_f32 v[30:31], v[30:31], v[32:33] op_sel_hi:[1,0]
	v_pk_mul_f32 v[28:29], v[28:29], v[32:33] op_sel_hi:[1,0]
	v_pk_mul_f32 v[26:27], v[26:27], v[32:33] op_sel_hi:[1,0]
	v_pk_mul_f32 v[24:25], v[24:25], v[32:33] op_sel_hi:[1,0]
	v_pk_mul_f32 v[22:23], v[22:23], v[32:33] op_sel_hi:[1,0]
	v_pk_mul_f32 v[20:21], v[20:21], v[32:33] op_sel_hi:[1,0]
	v_pk_mul_f32 v[18:19], v[18:19], v[32:33] op_sel_hi:[1,0]
	v_pk_mul_f32 v[16:17], v[16:17], v[32:33] op_sel_hi:[1,0]
	v_cvt_pk_bf16_f32 v32, v53, v55
	v_cvt_pk_bf16_f32 v33, v186, v184
	v_cvt_pk_bf16_f32 v34, v182, v180
	v_cvt_pk_bf16_f32 v35, v178, v64
	s_waitcnt lgkmcnt(3)
; #define LAS __attribute__((address_space(3)))
; __device__ __forceinline__ void attn_phase(CArgs a, int l, LAS unsigned char* lds, int tid, int lane, int wave, int G, int bx) {
;     ...
;                     for (int st = 0; st < 4; ++st) { const bf16x8 kf = *(const LAS bf16x8*)(Ks + (kvh * 192 + tt * 32 + ql) * 72 + st * 16 + hf * 8);
;                         sa = __builtin_amdgcn_mfma_f32_32x32x16_bf16(kf, qf[st], sa, 0, 0, 0); }
; #pragma unroll
;                     for (int i = 0; i < 16; ++i) sv[t3][i] = sa[i]; }
;                 float mn = mx;
; #pragma unroll
;                 for (int t3 = 0; t3 < 1; ++t3)
; #pragma unroll
;                     for (int i = 0; i < 16; ++i) { const int s = (ps + t3) * 32 + crow(i, hf); float v = sv[t3][i] + blh[s]; if (s < nmask) v = -1e30f; sv[t3][i] = v; mn = fmaxf(mn, v); }
;                 mn = fmaxf(mn, __shfl_xor(mn, 32));
;                 const float resc = __expf(mx - mn); mx = mn;
;                 float psum = 0.f;
; #pragma unroll
;                 for (int t3 = 0; t3 < 1; ++t3)
; #pragma unroll
;                     for (int i = 0; i < 16; ++i) { const float p = __expf(sv[t3][i] - mx); sv[t3][i] = p; psum += p; }
;                 sum = sum * resc + psum;
;                 o0 = o0 * resc; o1 = o1 * resc;
; #pragma unroll
;                 for (int t3 = 0; t3 < 1; ++t3)
; #pragma unroll
;                     for (int bb = 0; bb < 2; ++bb) { const int tt = ps + t3;
;                         u32x4 pw; pw.x = pk2(sv[t3][8 * bb], sv[t3][8 * bb + 1]); pw.y = pk2(sv[t3][8 * bb + 2], sv[t3][8 * bb + 3]); pw.z = pk2(sv[t3][8 * bb + 4], sv[t3][8 * bb + 5]); pw.w = pk2(sv[t3][8 * bb + 6], sv[t3][8 * bb + 7]);
;                         const bf16x8 pf = __builtin_bit_cast(bf16x8, pw);
;                         const LAS bf16_t* v0p = Vt + (kvh * 64 + ql) * 200 + tt * 32 + 16 * bb + 4 * hf;
;                         const LAS bf16_t* v1p = v0p + 32 * 200;
;                         u32x4 a0, a1; { const u32x2 lo = *(const LAS u32x2*)v0p, hi = *(const LAS u32x2*)(v0p + 8); a0.x = lo.x; a0.y = lo.y; a0.z = hi.x; a0.w = hi.y; }
;                         { const u32x2 lo = *(const LAS u32x2*)v1p, hi = *(const LAS u32x2*)(v1p + 8); a1.x = lo.x; a1.y = lo.y; a1.z = hi.x; a1.w = hi.y; }
;                         o0 = __builtin_amdgcn_mfma_f32_32x32x16_bf16(__builtin_bit_cast(bf16x8, a0), pf, o0, 0, 0, 0);
	s_nop 0
	v_mfma_f32_32x32x16_bf16 v[0:15], v[36:39], v[32:35], v[0:15]
	s_waitcnt lgkmcnt(1)
	v_mfma_f32_32x32x16_bf16 v[16:31], v[44:47], v[32:35], v[16:31]
	v_cvt_pk_bf16_f32 v32, v62, v60
	v_cvt_pk_bf16_f32 v33, v58, v56
	v_cvt_pk_bf16_f32 v34, v54, v52
	v_cvt_pk_bf16_f32 v35, v50, v48
	s_nop 1
	v_mfma_f32_32x32x16_bf16 v[0:15], v[40:43], v[32:35], v[0:15]
	s_waitcnt lgkmcnt(0)
	v_mfma_f32_32x32x16_bf16 v[16:31], v[190:193], v[32:35], v[16:31]
	v_add_f32_e32 v32, 0, v53
	v_add_f32_e32 v160, v55, v32
	ds_read_b128 v[32:35], v213 offset:23040
	ds_read_b128 v[190:193], v213 offset:23072
	ds_read_b128 v[92:95], v213 offset:23104
	ds_read_b128 v[96:99], v213 offset:23136
	ds_read2_b32 v[100:101], v229 offset0:223 offset1:224
	ds_read2_b32 v[102:103], v229 offset0:225 offset1:226
	ds_read2_b32 v[104:105], v229 offset0:231 offset1:232
	ds_read2_b32 v[106:107], v229 offset0:233 offset1:234
	ds_read2_b32 v[108:109], v229 offset0:239 offset1:240
	ds_read2_b32 v[110:111], v229 offset0:241 offset1:242
	ds_read2_b32 v[112:113], v229 offset0:247 offset1:248
	ds_read2_b32 v[90:91], v229 offset0:249 offset1:250
	s_waitcnt lgkmcnt(11)
	v_mfma_f32_32x32x16_bf16 v[32:47], v[32:35], v[138:141], 0
	s_waitcnt lgkmcnt(10)
	v_mfma_f32_32x32x16_bf16 v[32:47], v[190:193], v[142:145], v[32:47]
	s_waitcnt lgkmcnt(9)
	v_mfma_f32_32x32x16_bf16 v[32:47], v[92:95], v[134:137], v[32:47]
	s_waitcnt lgkmcnt(8)
	v_mfma_f32_32x32x16_bf16 v[32:47], v[96:99], v[130:133], v[32:47]
	s_waitcnt lgkmcnt(0)
	s_nop 10
	v_add_f32_e32 v51, v32, v100
	v_add_f32_e32 v53, v33, v101
	v_max3_f32 v55, v49, v51, v53
	s_waitcnt lgkmcnt(0)
	v_add_f32_e32 v34, v34, v102
	v_add_f32_e32 v35, v35, v103
	v_max3_f32 v55, v55, v34, v35
	s_waitcnt lgkmcnt(0)
	v_add_f32_e32 v36, v36, v104
	v_add_f32_e32 v37, v37, v105
	v_max3_f32 v55, v55, v36, v37
	s_waitcnt lgkmcnt(0)
	v_add_f32_e32 v38, v38, v106
	v_add_f32_e32 v39, v39, v107
	v_max3_f32 v55, v55, v38, v39
	s_waitcnt lgkmcnt(0)
	v_add_f32_e32 v40, v40, v108
	v_add_f32_e32 v41, v41, v109
	v_max3_f32 v55, v55, v40, v41
	s_waitcnt lgkmcnt(0)
	v_add_f32_e32 v42, v42, v110
	v_add_f32_e32 v43, v43, v111
	v_max3_f32 v55, v55, v42, v43
	s_waitcnt lgkmcnt(0)
	v_add_f32_e32 v44, v44, v112
	v_add_f32_e32 v45, v45, v113
	v_max3_f32 v55, v55, v44, v45
	s_waitcnt lgkmcnt(0)
	v_add_f32_e32 v32, v46, v90
	v_add_f32_e32 v33, v47, v91
	v_max3_f32 v46, v55, v32, v33
	ds_bpermute_b32 v47, v171, v46
	s_waitcnt lgkmcnt(0)
	v_max_f32_e32 v47, v47, v47
	v_max_f32_e32 v131, v46, v47
	v_sub_f32_e32 v34, v34, v131
	v_mul_f32_e32 v34, 0x3fb8aa3b, v34
	v_exp_f32_e32 v183, v34
	v_sub_f32_e32 v34, v35, v131
	v_mul_f32_e32 v34, 0x3fb8aa3b, v34
	v_exp_f32_e32 v181, v34
	v_sub_f32_e32 v34, v36, v131
	v_mul_f32_e32 v34, 0x3fb8aa3b, v34
	v_exp_f32_e32 v179, v34
	v_sub_f32_e32 v34, v37, v131
	v_mul_f32_e32 v34, 0x3fb8aa3b, v34
	v_exp_f32_e32 v65, v34
	v_sub_f32_e32 v34, v38, v131
	v_mul_f32_e32 v34, 0x3fb8aa3b, v34
	v_exp_f32_e32 v63, v34
	v_sub_f32_e32 v34, v39, v131
	v_mul_f32_e32 v34, 0x3fb8aa3b, v34
	v_exp_f32_e32 v61, v34
	v_sub_f32_e32 v34, v40, v131
	v_mul_f32_e32 v34, 0x3fb8aa3b, v34
	v_exp_f32_e32 v59, v34
	v_sub_f32_e32 v34, v41, v131
	v_mul_f32_e32 v34, 0x3fb8aa3b, v34
	v_sub_f32_e32 v46, v49, v131
	v_exp_f32_e32 v57, v34
	v_sub_f32_e32 v34, v42, v131
	v_mul_f32_e32 v46, 0x3fb8aa3b, v46
	v_sub_f32_e32 v47, v51, v131
	v_mul_f32_e32 v34, 0x3fb8aa3b, v34
	v_mul_f32_e32 v47, 0x3fb8aa3b, v47
	v_exp_f32_e32 v55, v34
	v_sub_f32_e32 v34, v43, v131
	v_exp_f32_e32 v130, v46
	v_exp_f32_e32 v187, v47
	v_sub_f32_e32 v47, v53, v131
	v_mul_f32_e32 v34, 0x3fb8aa3b, v34
	v_mul_f32_e32 v47, 0x3fb8aa3b, v47
	v_exp_f32_e32 v53, v34
	v_sub_f32_e32 v34, v44, v131
	v_exp_f32_e32 v185, v47
	v_mul_f32_e32 v34, 0x3fb8aa3b, v34
	v_sub_f32_e32 v32, v32, v131
	v_exp_f32_e32 v51, v34
	v_sub_f32_e32 v34, v45, v131
	v_mul_f32_e32 v32, 0x3fb8aa3b, v32
	v_pk_mul_f32 v[46:47], v[14:15], v[130:131] op_sel_hi:[1,0]
	v_pk_mul_f32 v[44:45], v[12:13], v[130:131] op_sel_hi:[1,0]
	v_pk_mul_f32 v[42:43], v[10:11], v[130:131] op_sel_hi:[1,0]
	v_pk_mul_f32 v[40:41], v[8:9], v[130:131] op_sel_hi:[1,0]
	v_pk_mul_f32 v[38:39], v[6:7], v[130:131] op_sel_hi:[1,0]
	v_pk_mul_f32 v[36:37], v[4:5], v[130:131] op_sel_hi:[1,0]
	v_pk_mul_f32 v[14:15], v[30:31], v[130:131] op_sel_hi:[1,0]
	v_pk_mul_f32 v[12:13], v[28:29], v[130:131] op_sel_hi:[1,0]
	v_pk_mul_f32 v[10:11], v[26:27], v[130:131] op_sel_hi:[1,0]
	v_pk_mul_f32 v[8:9], v[24:25], v[130:131] op_sel_hi:[1,0]
	v_pk_mul_f32 v[6:7], v[22:23], v[130:131] op_sel_hi:[1,0]
	v_pk_mul_f32 v[4:5], v[20:21], v[130:131] op_sel_hi:[1,0]
	ds_read2_b64 v[20:23], v153 offset0:40 offset1:42
	ds_read2_b64 v[24:27], v153 offset0:44 offset1:46
	ds_read2_b64 v[28:31], v230 offset0:104 offset1:106
	ds_read2_b64 v[132:135], v230 offset0:108 offset1:110
	v_exp_f32_e32 v189, v32
	v_sub_f32_e32 v32, v33, v131
	v_mul_f32_e32 v34, 0x3fb8aa3b, v34
	v_mul_f32_e32 v32, 0x3fb8aa3b, v32
	v_exp_f32_e32 v49, v34
	v_exp_f32_e32 v136, v32
	v_pk_mul_f32 v[34:35], v[2:3], v[130:131] op_sel_hi:[1,0]
	v_pk_mul_f32 v[32:33], v[0:1], v[130:131] op_sel_hi:[1,0]
	v_pk_mul_f32 v[2:3], v[18:19], v[130:131] op_sel_hi:[1,0]
	v_pk_mul_f32 v[0:1], v[16:17], v[130:131] op_sel_hi:[1,0]
	v_cvt_pk_bf16_f32 v16, v187, v185
	v_cvt_pk_bf16_f32 v17, v183, v181
	v_cvt_pk_bf16_f32 v18, v179, v65
	v_cvt_pk_bf16_f32 v19, v63, v61
	s_waitcnt lgkmcnt(3)
	s_nop 0
	v_mfma_f32_32x32x16_bf16 v[32:47], v[20:23], v[16:19], v[32:47]
	s_waitcnt lgkmcnt(1)
; __device__ __forceinline__ unsigned pk2(float lo, float hi) { const f32x2 v = {lo, hi}; return __builtin_bit_cast(unsigned, __builtin_convertvector(v, bf16x2_t)); }
; __device__ __forceinline__ void attn_phase(CArgs a, int l, LAS unsigned char* lds, int tid, int lane, int wave, int G, int bx) {
;     ...
;                         o0 = __builtin_amdgcn_mfma_f32_32x32x16_bf16(__builtin_bit_cast(bf16x8, a0), pf, o0, 0, 0, 0);
;                         o1 = __builtin_amdgcn_mfma_f32_32x32x16_bf16(__builtin_bit_cast(bf16x8, a1), pf, o1, 0, 0, 0);
;                     }
;             }
;             sum += __shfl_xor(sum, 32);
;             const float inv = 1.0f / (sum + __expf(sink - mx));
;             o0 = o0 * inv; o1 = o1 * inv;
; #pragma unroll
;             for (int i = 0; i < 16; ++i) ssq += o0[i] * o0[i] + o1[i] * o1[i];
; #pragma unroll
;             for (int i4 = 0; i4 < 4; ++i4) { const int col = 512 + h * 64 + 8 * i4 + 4 * hf;
;                 u32x2 w; w.x = pk2(o0[4 * i4], o0[4 * i4 + 1]); w.y = pk2(o0[4 * i4 + 2], o0[4 * i4 + 3]); *(u32x2*)(YC + (size_t)qtok * D + col) = w;
;                 u32x2 w2; w2.x = pk2(o1[4 * i4], o1[4 * i4 + 1]); w2.y = pk2(o1[4 * i4 + 2], o1[4 * i4 + 3]); *(u32x2*)(YC + (size_t)qtok * D + col + 32) = w2; }
;         }
;         ssq += __shfl_xor(ssq, 32);
;         if (lane < 32) RED[wave * 32 + ql] = ssq;
	v_mfma_f32_32x32x16_bf16 v[0:15], v[28:31], v[16:19], v[0:15]
	v_cvt_pk_bf16_f32 v16, v59, v57
	v_cvt_pk_bf16_f32 v17, v55, v53
	v_cvt_pk_bf16_f32 v18, v51, v49
	v_cvt_pk_bf16_f32 v19, v189, v136
	s_nop 1
	v_mfma_f32_32x32x16_bf16 v[32:47], v[24:27], v[16:19], v[32:47]
	s_waitcnt lgkmcnt(0)
	v_mfma_f32_32x32x16_bf16 v[0:15], v[132:135], v[16:19], v[0:15]
	v_add_f32_e64 v16, v186, v160
	v_add_f32_e64 v17, v187, v161
	v_add_f32_e64 v16, v184, v16
	v_add_f32_e64 v17, v185, v17
	v_add_f32_e64 v16, v182, v16
	v_add_f32_e64 v17, v183, v17
	v_pk_add_f32 v[16:17], v[180:181], v[16:17]
	s_nop 0
	v_pk_add_f32 v[16:17], v[178:179], v[16:17]
	s_nop 0
	v_pk_add_f32 v[16:17], v[64:65], v[16:17]
	s_nop 0
	v_pk_add_f32 v[16:17], v[62:63], v[16:17]
	s_nop 0
	v_pk_add_f32 v[16:17], v[60:61], v[16:17]
	s_nop 0
	v_pk_add_f32 v[16:17], v[58:59], v[16:17]
	s_nop 0
	v_pk_add_f32 v[16:17], v[56:57], v[16:17]
	s_nop 0
	v_pk_add_f32 v[16:17], v[54:55], v[16:17]
	s_nop 0
	v_pk_add_f32 v[16:17], v[52:53], v[16:17]
	s_nop 0
	v_pk_add_f32 v[16:17], v[50:51], v[16:17]
	s_nop 0
	v_pk_add_f32 v[16:17], v[48:49], v[16:17]
	s_nop 0
	v_pk_add_f32 v[16:17], v[188:189], v[16:17]
	s_nop 0
	v_add_f32_e32 v17, v17, v136
	v_fmac_f32_e32 v17, v16, v130
	ds_bpermute_b32 v16, v171, v17
	s_waitcnt lgkmcnt(0)
	v_add_f32_e32 v16, v17, v16
	v_sub_f32_e32 v17, v228, v131
	v_mul_f32_e32 v17, 0x3fb8aa3b, v17
	v_exp_f32_e32 v17, v17
	s_nop 0
	v_add_f32_e32 v16, v17, v16
	v_div_scale_f32 v17, s[90:91], v16, v16, 1.0
	v_rcp_f32_e32 v18, v17
	s_mov_b32 s90, 1
	v_fma_f32 v19, -v17, v18, 1.0
	v_fmac_f32_e32 v18, v19, v18
	v_div_scale_f32 v19, vcc, 1.0, v16, 1.0
	v_mul_f32_e32 v20, v19, v18
	v_fma_f32 v21, -v17, v20, v19
	v_fmac_f32_e32 v20, v21, v18
	v_fma_f32 v17, -v17, v20, v19
	v_div_fmas_f32 v17, v17, v18, v20
	v_div_fixup_f32 v24, v17, v16, 1.0
	v_pk_mul_f32 v[16:17], v[44:45], v[24:25] op_sel_hi:[1,0]
	v_or_b32_e32 v44, 0x200, v148
	v_pk_mul_f32 v[26:27], v[36:37], v[24:25] op_sel_hi:[1,0]
	v_pk_mul_f32 v[28:29], v[38:39], v[24:25] op_sel_hi:[1,0]
	v_pk_mul_f32 v[36:37], v[2:3], v[24:25] op_sel_hi:[1,0]
	v_pk_mul_f32 v[38:39], v[0:1], v[24:25] op_sel_hi:[1,0]
	v_lshl_add_u32 v44, s2, 6, v44
	v_pk_mul_f32 v[20:21], v[40:41], v[24:25] op_sel_hi:[1,0]
	v_pk_mul_f32 v[22:23], v[42:43], v[24:25] op_sel_hi:[1,0]
	v_pk_mul_f32 v[18:19], v[46:47], v[24:25] op_sel_hi:[1,0]
	v_pk_mul_f32 v[40:41], v[34:35], v[24:25] op_sel_hi:[1,0]
	v_pk_mul_f32 v[42:43], v[32:33], v[24:25] op_sel_hi:[1,0]
	v_pk_mul_f32 v[10:11], v[10:11], v[24:25] op_sel_hi:[1,0]
	v_pk_mul_f32 v[8:9], v[8:9], v[24:25] op_sel_hi:[1,0]
	v_mul_f32_e32 v46, v38, v38
	v_mul_f32_e32 v47, v39, v39
	v_mul_f32_e32 v48, v36, v36
	v_mul_f32_e32 v49, v37, v37
	v_ashrrev_i32_e32 v45, 31, v44
	v_pk_mul_f32 v[32:33], v[6:7], v[24:25] op_sel_hi:[1,0]
	v_fmac_f32_e32 v46, v42, v42
	v_fmac_f32_e32 v47, v43, v43
	v_fmac_f32_e32 v48, v40, v40
	v_fmac_f32_e32 v49, v41, v41
	v_pk_mul_f32 v[6:7], v[8:9], v[8:9]
	v_cvt_pk_bf16_f32 v42, v42, v43
	v_cvt_pk_bf16_f32 v43, v40, v41
	v_lshl_add_u64 v[40:41], v[44:45], 1, v[176:177]
	v_cvt_pk_bf16_f32 v8, v8, v9
	v_cvt_pk_bf16_f32 v9, v10, v11
	v_pk_mul_f32 v[14:15], v[14:15], v[24:25] op_sel_hi:[1,0]
	v_pk_mul_f32 v[12:13], v[12:13], v[24:25] op_sel_hi:[1,0]
	global_store_dwordx2 v[40:41], v[8:9], off offset:96
	v_cvt_pk_bf16_f32 v8, v16, v17
	v_cvt_pk_bf16_f32 v9, v18, v19
	global_store_dwordx2 v[40:41], v[8:9], off offset:48
	v_cvt_pk_bf16_f32 v8, v12, v13
	v_cvt_pk_bf16_f32 v9, v14, v15
	global_store_dwordx2 v[40:41], v[8:9], off offset:112
	v_add_f32_e32 v8, v226, v46
	v_pk_mul_f32 v[34:35], v[4:5], v[24:25] op_sel_hi:[1,0]
	v_add_f32_e32 v8, v47, v8
	v_pk_mul_f32 v[30:31], v[34:35], v[34:35]
	v_add_f32_e32 v8, v48, v8
	v_pk_fma_f32 v[30:31], v[26:27], v[26:27], v[30:31]
	v_add_f32_e32 v8, v49, v8
	v_pk_mul_f32 v[24:25], v[32:33], v[32:33]
	v_add_f32_e32 v8, v30, v8
	v_pk_fma_f32 v[24:25], v[28:29], v[28:29], v[24:25]
	v_add_f32_e32 v8, v31, v8
	v_add_f32_e32 v8, v24, v8
	v_pk_fma_f32 v[6:7], v[20:21], v[20:21], v[6:7]
	v_add_f32_e32 v8, v25, v8
	v_pk_mul_f32 v[4:5], v[10:11], v[10:11]
	v_add_f32_e32 v6, v6, v8
	v_pk_fma_f32 v[4:5], v[22:23], v[22:23], v[4:5]
	v_add_f32_e32 v6, v7, v6
	v_pk_mul_f32 v[2:3], v[12:13], v[12:13]
	v_add_f32_e32 v4, v4, v6
	v_pk_fma_f32 v[2:3], v[16:17], v[16:17], v[2:3]
	v_add_f32_e32 v4, v5, v4
	v_pk_mul_f32 v[0:1], v[14:15], v[14:15]
	v_add_f32_e32 v2, v2, v4
	v_pk_fma_f32 v[0:1], v[18:19], v[18:19], v[0:1]
	v_add_f32_e32 v2, v3, v2
	v_cvt_pk_bf16_f32 v26, v26, v27
	v_cvt_pk_bf16_f32 v27, v28, v29
	v_add_f32_e32 v0, v0, v2
	v_cvt_pk_bf16_f32 v38, v38, v39
	v_cvt_pk_bf16_f32 v39, v36, v37
	global_store_dwordx2 v[40:41], v[26:27], off offset:16
	v_cvt_pk_bf16_f32 v26, v34, v35
	v_cvt_pk_bf16_f32 v27, v32, v33
	v_cvt_pk_bf16_f32 v20, v20, v21
	v_cvt_pk_bf16_f32 v21, v22, v23
	v_add_f32_e32 v226, v1, v0
	s_mov_b64 s[2:3], 0
	s_and_b64 vcc, exec, s[88:89]
	global_store_dwordx2 v[40:41], v[42:43], off
	global_store_dwordx2 v[40:41], v[38:39], off offset:64
	global_store_dwordx2 v[40:41], v[26:27], off offset:80
	global_store_dwordx2 v[40:41], v[20:21], off offset:32
	s_cbranch_vccz .LBB0_357
	ds_bpermute_b32 v0, v171, v226
	s_mov_b64 s[0:1], exec
	v_readlane_b32 s2, v255, 30
	v_readlane_b32 s3, v255, 31
	s_and_b64 s[2:3], s[0:1], s[2:3]
	s_mov_b32 s81, 0x8000
	s_mov_b32 s84, 0xc000
	s_movk_i32 s85, 0xa00
	s_movk_i32 s86, 0x1000
	s_movk_i32 s87, 0x1ff
	s_movk_i32 s88, 0xdff
	s_movk_i32 s89, 0x7f
	s_mov_b64 exec, s[2:3]
	s_cbranch_execz .LBB0_276
	s_waitcnt lgkmcnt(0)
	v_add_f32_e32 v0, v226, v0
	ds_write_b32 v225, v0
	s_branch .LBB0_276

; #define PG8_STAGE(bufoff, gbase, voff) do { _Pragma("unroll") for (int _i = 0; _i < 2; ++_i) \
;         __builtin_amdgcn_global_load_lds((const unsigned*)((const char*)(gbase) + (voff)[_i]), (LAS unsigned*)(lds + (bufoff) + ldsw + _i * 8192), 16, 0, 0); } while (0)
; #define PG8_STAGEA(bufoff, gbase, voff) do { _Pragma("unroll") for (int _i = 0; _i < 2; ++_i) \
;         __builtin_amdgcn_global_load_lds((const unsigned*)((const char*)(gbase) + (voff)[_i]), (LAS unsigned*)(lds + (bufoff) + ldsw + _i * 8192), 16, 0, AUXA); } while (0)
; #define PG8_LDA(dst, b, h) do { _Pragma("unroll") for (int m = 0; m < 4; ++m) _Pragma("unroll") for (int k = 0; k < 2; ++k) dst[m][k] = *(const LAS bf16x8*)(lds + PG8_SA(b, h) + aoff + m * 2048 + k * 1024); } while (0)
; #define PG8_LDB(dst, b, h) do { _Pragma("unroll") for (int n = 0; n < 2; ++n) _Pragma("unroll") for (int k = 0; k < 2; ++k) dst[n][k] = *(const LAS bf16x8*)(lds + PG8_SB(b, h) + boff + n * 2048 + k * 1024); } while (0)
; #define PG8_MMA(ai, bj, At, Bt) do { __builtin_amdgcn_s_setprio(1); _Pragma("unroll") for (int m = 0; m < 4; ++m) _Pragma("unroll") for (int n = 0; n < 2; ++n) _Pragma("unroll") for (int k = 0; k < 2; ++k) \
;         acc[ai][bj][m][n] = __builtin_amdgcn_mfma_f32_16x16x32_bf16(Bt[n][k], At[m][k], acc[ai][bj][m][n], 0, 0, 0); __builtin_amdgcn_s_setprio(0); } while (0)
; #define PG8_WAIT_V(n) asm volatile("s_waitcnt vmcnt(" #n ")" ::: "memory")
; #define PG8_WAIT_L(n) asm volatile("s_waitcnt lgkmcnt(" #n ")" ::: "memory")
; #define PG8_BAR __builtin_amdgcn_s_barrier()
; #define PG8_SCHED __builtin_amdgcn_sched_barrier(0)
;     ...
;             PG8_LDB(B0, 0, 0); PG8_LDB(B1, 0, 1); PG8_SCHED; PG8_LDA(At, 0, 0); PG8_STAGEA(PG8_SA(1, 1), a1 + hstepA, voffA);
;             PG8_WAIT_V(8); PG8_WAIT_L(0); PG8_BAR; PG8_MMA(0, 0, At, B0); PG8_MMA(0, 1, At, B1); PG8_BAR; PG8_SCHED;
;             PG8_LDA(At, 0, 1); PG8_STAGE(PG8_SB(0, 0), b2, voffB); PG8_STAGE(PG8_SB(0, 1), b2 + hstepB, voffB); PG8_STAGEA(PG8_SA(0, 0), a2, voffA);
;             PG8_WAIT_V(8); PG8_WAIT_L(0); PG8_BAR; PG8_MMA(1, 0, At, B0); PG8_MMA(1, 1, At, B1); PG8_BAR; PG8_SCHED;
.LBB0_503:
	s_add_u32 s16, s0, 0xfff80080
	s_addc_u32 s17, s1, -1
	s_add_i32 s44, 0, 0x10000
	s_cmp_eq_u32 s43, 28
	s_cselect_b32 s19, s37, s17
	s_cselect_b32 s18, s38, s16
	v_add_u32_e32 v140, s44, v146
	s_cselect_b32 s17, s39, s42
	s_cselect_b32 s16, s40, s41
	s_add_i32 s46, 0, 0x14000
	ds_read_b128 v[148:151], v140
	ds_read_b128 v[152:155], v140 offset:1024
	ds_read_b128 v[156:159], v140 offset:2048
	ds_read_b128 v[168:171], v140 offset:3072
	v_add_u32_e32 v140, s46, v146
	ds_read_b128 v[172:175], v140
	ds_read_b128 v[176:179], v140 offset:1024
	ds_read_b128 v[180:183], v140 offset:2048
	ds_read_b128 v[184:187], v140 offset:3072
	s_add_u32 s62, s0, 0xfff80000
	s_addc_u32 s63, s1, -1
	v_lshl_add_u64 v[232:233], s[62:63], 0, v[136:137]
	s_mov_b32 m0, s23
	s_nop 0
	global_load_lds_dwordx4 v[232:233], off
	v_lshl_add_u64 v[232:233], s[62:63], 0, v[138:139]
	s_mov_b32 m0, s24
	s_nop 0
	global_load_lds_dwordx4 v[232:233], off
	v_lshl_add_u64 v[140:141], s[0:1], 0, v[136:137]
	s_add_i32 m0, s7, 0xc000
	ds_read_b128 v[188:191], v142
	ds_read_b128 v[192:195], v142 offset:1024
	ds_read_b128 v[196:199], v142 offset:2048
	ds_read_b128 v[200:203], v142 offset:3072
	ds_read_b128 v[204:207], v142 offset:4096
	ds_read_b128 v[208:211], v142 offset:5120
	ds_read_b128 v[220:223], v142 offset:6144
	ds_read_b128 v[224:227], v142 offset:7168
	global_load_lds_dwordx4 v[140:141], off
	v_lshl_add_u64 v[140:141], s[0:1], 0, v[138:139]
	s_add_i32 m0, s7, 0xe000
	s_nop 0
	global_load_lds_dwordx4 v[140:141], off
	s_waitcnt vmcnt(8)
	s_waitcnt lgkmcnt(0)
	s_barrier
	s_nop 0
	s_waitcnt lgkmcnt(0)
	v_mfma_f32_16x16x32_bf16 v[124:127], v[148:151], v[188:191], v[124:127]
	v_mfma_f32_16x16x32_bf16 v[120:123], v[156:159], v[188:191], v[120:123]
	v_mfma_f32_16x16x32_bf16 v[108:111], v[148:151], v[196:199], v[108:111]
	v_mfma_f32_16x16x32_bf16 v[104:107], v[156:159], v[196:199], v[104:107]
	v_mfma_f32_16x16x32_bf16 v[92:95], v[148:151], v[204:207], v[92:95]
	v_mfma_f32_16x16x32_bf16 v[88:91], v[156:159], v[204:207], v[88:91]
	v_mfma_f32_16x16x32_bf16 v[76:79], v[148:151], v[220:223], v[76:79]
	v_mfma_f32_16x16x32_bf16 v[72:75], v[156:159], v[220:223], v[72:75]
	v_mfma_f32_16x16x32_bf16 v[124:127], v[152:155], v[192:195], v[124:127]
	v_mfma_f32_16x16x32_bf16 v[120:123], v[168:171], v[192:195], v[120:123]
	v_mfma_f32_16x16x32_bf16 v[108:111], v[152:155], v[200:203], v[108:111]
	v_mfma_f32_16x16x32_bf16 v[104:107], v[168:171], v[200:203], v[104:107]
	v_mfma_f32_16x16x32_bf16 v[92:95], v[152:155], v[208:211], v[92:95]
	v_mfma_f32_16x16x32_bf16 v[88:91], v[168:171], v[208:211], v[88:91]
	v_mfma_f32_16x16x32_bf16 v[76:79], v[152:155], v[224:227], v[76:79]
	v_mfma_f32_16x16x32_bf16 v[72:75], v[168:171], v[224:227], v[72:75]
	s_nop 0
	s_nop 0
	v_mfma_f32_16x16x32_bf16 v[116:119], v[172:175], v[188:191], v[116:119]
	v_mfma_f32_16x16x32_bf16 v[112:115], v[180:183], v[188:191], v[112:115]
	v_mfma_f32_16x16x32_bf16 v[100:103], v[172:175], v[196:199], v[100:103]
	v_mfma_f32_16x16x32_bf16 v[96:99], v[180:183], v[196:199], v[96:99]
	v_mfma_f32_16x16x32_bf16 v[84:87], v[172:175], v[204:207], v[84:87]
	v_mfma_f32_16x16x32_bf16 v[80:83], v[180:183], v[204:207], v[80:83]
	v_mfma_f32_16x16x32_bf16 v[68:71], v[172:175], v[220:223], v[68:71]
	v_mfma_f32_16x16x32_bf16 v[64:67], v[180:183], v[220:223], v[64:67]
	v_mfma_f32_16x16x32_bf16 v[116:119], v[176:179], v[192:195], v[116:119]
	v_mfma_f32_16x16x32_bf16 v[112:115], v[184:187], v[192:195], v[112:115]
	v_mfma_f32_16x16x32_bf16 v[100:103], v[176:179], v[200:203], v[100:103]
	v_mfma_f32_16x16x32_bf16 v[96:99], v[184:187], v[200:203], v[96:99]
	v_mfma_f32_16x16x32_bf16 v[84:87], v[176:179], v[208:211], v[84:87]
	v_mfma_f32_16x16x32_bf16 v[80:83], v[184:187], v[208:211], v[80:83]
	v_mfma_f32_16x16x32_bf16 v[68:71], v[176:179], v[224:227], v[68:71]
	v_mfma_f32_16x16x32_bf16 v[64:67], v[184:187], v[224:227], v[64:67]
	s_nop 0
	s_barrier
	s_add_i32 s44, s44, s2
	v_lshl_add_u64 v[140:141], s[16:17], 0, v[160:161]
	s_mov_b32 m0, s44
	ds_read_b128 v[188:191], v142 offset:16384
	ds_read_b128 v[192:195], v142 offset:17408
	ds_read_b128 v[196:199], v142 offset:18432
	ds_read_b128 v[200:203], v142 offset:19456
	ds_read_b128 v[204:207], v142 offset:20480
	ds_read_b128 v[208:211], v142 offset:21504
	ds_read_b128 v[220:223], v142 offset:22528
	ds_read_b128 v[224:227], v142 offset:23552
	global_load_lds_dwordx4 v[140:141], off
	s_add_i32 m0, s44, 0x2000
	s_add_u32 s44, s16, 0x80000
	v_lshl_add_u64 v[144:145], s[16:17], 0, v[132:133]
	s_addc_u32 s45, s17, 0
	s_add_i32 s46, s46, s2
	global_load_lds_dwordx4 v[144:145], off
	v_lshl_add_u64 v[212:213], s[44:45], 0, v[160:161]
	s_mov_b32 m0, s46
	v_lshl_add_u64 v[228:229], s[18:19], 0, v[130:131]
	global_load_lds_dwordx4 v[212:213], off
	v_lshl_add_u64 v[212:213], s[44:45], 0, v[132:133]
	s_add_i32 m0, s46, 0x2000
	s_nop 0
	global_load_lds_dwordx4 v[212:213], off
	s_waitcnt vmcnt(6)
	s_waitcnt lgkmcnt(0)
	s_barrier
; #define PG8_STAGE(bufoff, gbase, voff) do { _Pragma("unroll") for (int _i = 0; _i < 2; ++_i) \
;         __builtin_amdgcn_global_load_lds((const unsigned*)((const char*)(gbase) + (voff)[_i]), (LAS unsigned*)(lds + (bufoff) + ldsw + _i * 8192), 16, 0, 0); } while (0)
; #define PG8_STAGEA(bufoff, gbase, voff) do { _Pragma("unroll") for (int _i = 0; _i < 2; ++_i) \
;         __builtin_amdgcn_global_load_lds((const unsigned*)((const char*)(gbase) + (voff)[_i]), (LAS unsigned*)(lds + (bufoff) + ldsw + _i * 8192), 16, 0, AUXA); } while (0)
; #define PG8_LDA(dst, b, h) do { _Pragma("unroll") for (int m = 0; m < 4; ++m) _Pragma("unroll") for (int k = 0; k < 2; ++k) dst[m][k] = *(const LAS bf16x8*)(lds + PG8_SA(b, h) + aoff + m * 2048 + k * 1024); } while (0)
; #define PG8_LDB(dst, b, h) do { _Pragma("unroll") for (int n = 0; n < 2; ++n) _Pragma("unroll") for (int k = 0; k < 2; ++k) dst[n][k] = *(const LAS bf16x8*)(lds + PG8_SB(b, h) + boff + n * 2048 + k * 1024); } while (0)
; #define PG8_MMA(ai, bj, At, Bt) do { __builtin_amdgcn_s_setprio(1); _Pragma("unroll") for (int m = 0; m < 4; ++m) _Pragma("unroll") for (int n = 0; n < 2; ++n) _Pragma("unroll") for (int k = 0; k < 2; ++k) \
;         acc[ai][bj][m][n] = __builtin_amdgcn_mfma_f32_16x16x32_bf16(Bt[n][k], At[m][k], acc[ai][bj][m][n], 0, 0, 0); __builtin_amdgcn_s_setprio(0); } while (0)
; #define PG8_WAIT_V(n) asm volatile("s_waitcnt vmcnt(" #n ")" ::: "memory")
; #define PG8_WAIT_L(n) asm volatile("s_waitcnt lgkmcnt(" #n ")" ::: "memory")
; #define PG8_BAR __builtin_amdgcn_s_barrier()
; #define PG8_SCHED __builtin_amdgcn_sched_barrier(0)
;     ...
;             PG8_WAIT_V(8); PG8_WAIT_L(0); PG8_BAR; PG8_MMA(1, 0, At, B0); PG8_MMA(1, 1, At, B1); PG8_BAR; PG8_SCHED;
;             PG8_LDB(B0, 1, 0); PG8_LDB(B1, 1, 1); PG8_SCHED; PG8_LDA(At, 1, 0); PG8_STAGEA(PG8_SA(0, 1), a2 + hstepA, voffA);
;             PG8_WAIT_V(8); PG8_WAIT_L(0); PG8_BAR; PG8_MMA(0, 0, At, B0); PG8_MMA(0, 1, At, B1); PG8_BAR; PG8_SCHED;
;             PG8_LDA(At, 1, 1); PG8_STAGE(PG8_SB(1, 0), b3, voffB); PG8_STAGE(PG8_SB(1, 1), b3 + hstepB, voffB); PG8_STAGEA(PG8_SA(1, 0), a3, voffA);
	s_nop 0
	s_waitcnt lgkmcnt(0)
	v_mfma_f32_16x16x32_bf16 v[60:63], v[148:151], v[188:191], v[60:63]
	v_mfma_f32_16x16x32_bf16 v[56:59], v[156:159], v[188:191], v[56:59]
	v_mfma_f32_16x16x32_bf16 v[44:47], v[148:151], v[196:199], v[44:47]
	v_mfma_f32_16x16x32_bf16 v[40:43], v[156:159], v[196:199], v[40:43]
	v_mfma_f32_16x16x32_bf16 v[28:31], v[148:151], v[204:207], v[28:31]
	v_mfma_f32_16x16x32_bf16 v[24:27], v[156:159], v[204:207], v[24:27]
	v_mfma_f32_16x16x32_bf16 v[12:15], v[148:151], v[220:223], v[12:15]
	v_mfma_f32_16x16x32_bf16 v[8:11], v[156:159], v[220:223], v[8:11]
	v_mfma_f32_16x16x32_bf16 v[60:63], v[152:155], v[192:195], v[60:63]
	v_mfma_f32_16x16x32_bf16 v[56:59], v[168:171], v[192:195], v[56:59]
	v_mfma_f32_16x16x32_bf16 v[44:47], v[152:155], v[200:203], v[44:47]
	v_mfma_f32_16x16x32_bf16 v[40:43], v[168:171], v[200:203], v[40:43]
	v_mfma_f32_16x16x32_bf16 v[28:31], v[152:155], v[208:211], v[28:31]
	v_mfma_f32_16x16x32_bf16 v[24:27], v[168:171], v[208:211], v[24:27]
	v_mfma_f32_16x16x32_bf16 v[12:15], v[152:155], v[224:227], v[12:15]
	v_mfma_f32_16x16x32_bf16 v[8:11], v[168:171], v[224:227], v[8:11]
	s_nop 0
	s_nop 0
	v_mfma_f32_16x16x32_bf16 v[52:55], v[172:175], v[188:191], v[52:55]
	v_mfma_f32_16x16x32_bf16 v[48:51], v[180:183], v[188:191], v[48:51]
	v_mfma_f32_16x16x32_bf16 v[36:39], v[172:175], v[196:199], v[36:39]
	v_mfma_f32_16x16x32_bf16 v[32:35], v[180:183], v[196:199], v[32:35]
	v_mfma_f32_16x16x32_bf16 v[20:23], v[172:175], v[204:207], v[20:23]
	v_mfma_f32_16x16x32_bf16 v[16:19], v[180:183], v[204:207], v[16:19]
	v_mfma_f32_16x16x32_bf16 v[4:7], v[172:175], v[220:223], v[4:7]
	v_mfma_f32_16x16x32_bf16 v[0:3], v[180:183], v[220:223], v[0:3]
	v_mfma_f32_16x16x32_bf16 v[52:55], v[176:179], v[192:195], v[52:55]
	v_mfma_f32_16x16x32_bf16 v[48:51], v[184:187], v[192:195], v[48:51]
	v_mfma_f32_16x16x32_bf16 v[36:39], v[176:179], v[200:203], v[36:39]
	v_mfma_f32_16x16x32_bf16 v[32:35], v[184:187], v[200:203], v[32:35]
	v_mfma_f32_16x16x32_bf16 v[20:23], v[176:179], v[208:211], v[20:23]
	v_mfma_f32_16x16x32_bf16 v[16:19], v[184:187], v[208:211], v[16:19]
	v_mfma_f32_16x16x32_bf16 v[4:7], v[176:179], v[224:227], v[4:7]
	v_mfma_f32_16x16x32_bf16 v[0:3], v[184:187], v[224:227], v[0:3]
	s_nop 0
	s_barrier
	s_add_i32 s44, 0, 0x18000
	v_add_u32_e32 v143, s44, v146
	s_add_i32 s45, 0, 0x1c000
	ds_read_b128 v[148:151], v143
	ds_read_b128 v[152:155], v143 offset:1024
	ds_read_b128 v[156:159], v143 offset:2048
	ds_read_b128 v[168:171], v143 offset:3072
	v_add_u32_e32 v143, s45, v146
	ds_read_b128 v[172:175], v143
	ds_read_b128 v[176:179], v143 offset:1024
	ds_read_b128 v[180:183], v143 offset:2048
	ds_read_b128 v[184:187], v143 offset:3072
	v_lshl_add_u64 v[232:233], s[18:19], 0, v[128:129]
	s_mov_b32 m0, s7
	s_nop 0
	global_load_lds_dwordx4 v[232:233], off
	v_lshl_add_u64 v[232:233], s[18:19], 0, v[130:131]
	s_mov_b32 m0, s20
	s_nop 0
	global_load_lds_dwordx4 v[232:233], off
	s_add_u32 s18, s18, 0x80000
	s_addc_u32 s19, s19, 0
	s_mov_b32 m0, s21
	v_lshl_add_u64 v[230:231], s[18:19], 0, v[128:129]
	ds_read_b128 v[188:191], v142 offset:32768
	ds_read_b128 v[192:195], v142 offset:33792
	ds_read_b128 v[196:199], v142 offset:34816
	ds_read_b128 v[200:203], v142 offset:35840
	ds_read_b128 v[204:207], v142 offset:36864
	ds_read_b128 v[208:211], v142 offset:37888
	ds_read_b128 v[220:223], v142 offset:38912
	ds_read_b128 v[224:227], v142 offset:39936
	global_load_lds_dwordx4 v[230:231], off
	v_lshl_add_u64 v[230:231], s[18:19], 0, v[130:131]
	s_mov_b32 m0, s22
	s_nop 0
	global_load_lds_dwordx4 v[230:231], off
	s_waitcnt vmcnt(8)
	s_waitcnt lgkmcnt(0)
	s_barrier
; #define PG8_STAGE(bufoff, gbase, voff) do { _Pragma("unroll") for (int _i = 0; _i < 2; ++_i) \
;         __builtin_amdgcn_global_load_lds((const unsigned*)((const char*)(gbase) + (voff)[_i]), (LAS unsigned*)(lds + (bufoff) + ldsw + _i * 8192), 16, 0, 0); } while (0)
; #define PG8_STAGEA(bufoff, gbase, voff) do { _Pragma("unroll") for (int _i = 0; _i < 2; ++_i) \
;         __builtin_amdgcn_global_load_lds((const unsigned*)((const char*)(gbase) + (voff)[_i]), (LAS unsigned*)(lds + (bufoff) + ldsw + _i * 8192), 16, 0, AUXA); } while (0)
; #define PG8_LDA(dst, b, h) do { _Pragma("unroll") for (int m = 0; m < 4; ++m) _Pragma("unroll") for (int k = 0; k < 2; ++k) dst[m][k] = *(const LAS bf16x8*)(lds + PG8_SA(b, h) + aoff + m * 2048 + k * 1024); } while (0)
; #define PG8_MMA(ai, bj, At, Bt) do { __builtin_amdgcn_s_setprio(1); _Pragma("unroll") for (int m = 0; m < 4; ++m) _Pragma("unroll") for (int n = 0; n < 2; ++n) _Pragma("unroll") for (int k = 0; k < 2; ++k) \
;         acc[ai][bj][m][n] = __builtin_amdgcn_mfma_f32_16x16x32_bf16(Bt[n][k], At[m][k], acc[ai][bj][m][n], 0, 0, 0); __builtin_amdgcn_s_setprio(0); } while (0)
; #define PG8_WAIT_V(n) asm volatile("s_waitcnt vmcnt(" #n ")" ::: "memory")
; #define PG8_WAIT_L(n) asm volatile("s_waitcnt lgkmcnt(" #n ")" ::: "memory")
; #define PG8_BAR __builtin_amdgcn_s_barrier()
; #define PG8_SCHED __builtin_amdgcn_sched_barrier(0)
;     ...
;             PG8_WAIT_V(8); PG8_WAIT_L(0); PG8_BAR; PG8_MMA(0, 0, At, B0); PG8_MMA(0, 1, At, B1); PG8_BAR; PG8_SCHED;
;             PG8_LDA(At, 1, 1); PG8_STAGE(PG8_SB(1, 0), b3, voffB); PG8_STAGE(PG8_SB(1, 1), b3 + hstepB, voffB); PG8_STAGEA(PG8_SA(1, 0), a3, voffA);
;             PG8_WAIT_V(8); PG8_WAIT_L(0); PG8_BAR; PG8_MMA(1, 0, At, B0); PG8_MMA(1, 1, At, B1); PG8_BAR; PG8_SCHED;
;         }
	s_nop 0
	s_waitcnt lgkmcnt(0)
	v_mfma_f32_16x16x32_bf16 v[124:127], v[148:151], v[188:191], v[124:127]
	v_mfma_f32_16x16x32_bf16 v[120:123], v[156:159], v[188:191], v[120:123]
	v_mfma_f32_16x16x32_bf16 v[108:111], v[148:151], v[196:199], v[108:111]
	v_mfma_f32_16x16x32_bf16 v[104:107], v[156:159], v[196:199], v[104:107]
	v_mfma_f32_16x16x32_bf16 v[92:95], v[148:151], v[204:207], v[92:95]
	v_mfma_f32_16x16x32_bf16 v[88:91], v[156:159], v[204:207], v[88:91]
	v_mfma_f32_16x16x32_bf16 v[76:79], v[148:151], v[220:223], v[76:79]
	v_mfma_f32_16x16x32_bf16 v[72:75], v[156:159], v[220:223], v[72:75]
	v_mfma_f32_16x16x32_bf16 v[124:127], v[152:155], v[192:195], v[124:127]
	v_mfma_f32_16x16x32_bf16 v[120:123], v[168:171], v[192:195], v[120:123]
	v_mfma_f32_16x16x32_bf16 v[108:111], v[152:155], v[200:203], v[108:111]
	v_mfma_f32_16x16x32_bf16 v[104:107], v[168:171], v[200:203], v[104:107]
	v_mfma_f32_16x16x32_bf16 v[92:95], v[152:155], v[208:211], v[92:95]
	v_mfma_f32_16x16x32_bf16 v[88:91], v[168:171], v[208:211], v[88:91]
	v_mfma_f32_16x16x32_bf16 v[76:79], v[152:155], v[224:227], v[76:79]
	v_mfma_f32_16x16x32_bf16 v[72:75], v[168:171], v[224:227], v[72:75]
	s_nop 0
	s_nop 0
	v_mfma_f32_16x16x32_bf16 v[116:119], v[172:175], v[188:191], v[116:119]
	v_mfma_f32_16x16x32_bf16 v[112:115], v[180:183], v[188:191], v[112:115]
	v_mfma_f32_16x16x32_bf16 v[100:103], v[172:175], v[196:199], v[100:103]
	v_mfma_f32_16x16x32_bf16 v[96:99], v[180:183], v[196:199], v[96:99]
	v_mfma_f32_16x16x32_bf16 v[84:87], v[172:175], v[204:207], v[84:87]
	v_mfma_f32_16x16x32_bf16 v[80:83], v[180:183], v[204:207], v[80:83]
	v_mfma_f32_16x16x32_bf16 v[68:71], v[172:175], v[220:223], v[68:71]
	v_mfma_f32_16x16x32_bf16 v[64:67], v[180:183], v[220:223], v[64:67]
	v_mfma_f32_16x16x32_bf16 v[116:119], v[176:179], v[192:195], v[116:119]
	v_mfma_f32_16x16x32_bf16 v[112:115], v[184:187], v[192:195], v[112:115]
	v_mfma_f32_16x16x32_bf16 v[100:103], v[176:179], v[200:203], v[100:103]
	v_mfma_f32_16x16x32_bf16 v[96:99], v[184:187], v[200:203], v[96:99]
	v_mfma_f32_16x16x32_bf16 v[84:87], v[176:179], v[208:211], v[84:87]
	v_mfma_f32_16x16x32_bf16 v[80:83], v[184:187], v[208:211], v[80:83]
	v_mfma_f32_16x16x32_bf16 v[68:71], v[176:179], v[224:227], v[68:71]
	v_mfma_f32_16x16x32_bf16 v[64:67], v[184:187], v[224:227], v[64:67]
	s_nop 0
	s_barrier
	s_add_i32 s18, s44, s2
	v_lshl_add_u64 v[140:141], v[140:141], 0, s[48:49]
	s_mov_b32 m0, s18
	ds_read_b128 v[188:191], v142 offset:49152
	ds_read_b128 v[192:195], v142 offset:50176
	ds_read_b128 v[196:199], v142 offset:51200
	ds_read_b128 v[200:203], v142 offset:52224
	ds_read_b128 v[204:207], v142 offset:53248
	ds_read_b128 v[208:211], v142 offset:54272
	ds_read_b128 v[220:223], v142 offset:55296
	ds_read_b128 v[224:227], v142 offset:56320
	global_load_lds_dwordx4 v[140:141], off
	s_add_i32 m0, s18, 0x2000
	s_add_u32 s16, s16, 0x80080
	v_lshl_add_u64 v[140:141], v[144:145], 0, s[48:49]
	s_addc_u32 s17, s17, 0
	s_add_i32 s18, s45, s2
	global_load_lds_dwordx4 v[140:141], off
	v_lshl_add_u64 v[140:141], s[16:17], 0, v[160:161]
	s_mov_b32 m0, s18
	s_nop 0
	global_load_lds_dwordx4 v[140:141], off
	v_lshl_add_u64 v[140:141], s[16:17], 0, v[132:133]
	s_add_i32 m0, s18, 0x2000
	s_nop 0
	global_load_lds_dwordx4 v[140:141], off
	s_waitcnt vmcnt(6)
	s_waitcnt lgkmcnt(0)
	s_barrier
	s_nop 0
	s_waitcnt lgkmcnt(0)
	v_mfma_f32_16x16x32_bf16 v[60:63], v[148:151], v[188:191], v[60:63]
	v_mfma_f32_16x16x32_bf16 v[56:59], v[156:159], v[188:191], v[56:59]
	v_mfma_f32_16x16x32_bf16 v[44:47], v[148:151], v[196:199], v[44:47]
	v_mfma_f32_16x16x32_bf16 v[40:43], v[156:159], v[196:199], v[40:43]
	v_mfma_f32_16x16x32_bf16 v[28:31], v[148:151], v[204:207], v[28:31]
	v_mfma_f32_16x16x32_bf16 v[24:27], v[156:159], v[204:207], v[24:27]
	v_mfma_f32_16x16x32_bf16 v[12:15], v[148:151], v[220:223], v[12:15]
	v_mfma_f32_16x16x32_bf16 v[8:11], v[156:159], v[220:223], v[8:11]
	v_mfma_f32_16x16x32_bf16 v[60:63], v[152:155], v[192:195], v[60:63]
	v_mfma_f32_16x16x32_bf16 v[56:59], v[168:171], v[192:195], v[56:59]
	v_mfma_f32_16x16x32_bf16 v[44:47], v[152:155], v[200:203], v[44:47]
	v_mfma_f32_16x16x32_bf16 v[40:43], v[168:171], v[200:203], v[40:43]
	v_mfma_f32_16x16x32_bf16 v[28:31], v[152:155], v[208:211], v[28:31]
	v_mfma_f32_16x16x32_bf16 v[24:27], v[168:171], v[208:211], v[24:27]
	v_mfma_f32_16x16x32_bf16 v[12:15], v[152:155], v[224:227], v[12:15]
	v_mfma_f32_16x16x32_bf16 v[8:11], v[168:171], v[224:227], v[8:11]
	s_nop 0
	s_nop 0
	v_mfma_f32_16x16x32_bf16 v[52:55], v[172:175], v[188:191], v[52:55]
	v_mfma_f32_16x16x32_bf16 v[48:51], v[180:183], v[188:191], v[48:51]
	v_mfma_f32_16x16x32_bf16 v[36:39], v[172:175], v[196:199], v[36:39]
	v_mfma_f32_16x16x32_bf16 v[32:35], v[180:183], v[196:199], v[32:35]
	v_mfma_f32_16x16x32_bf16 v[20:23], v[172:175], v[204:207], v[20:23]
	v_mfma_f32_16x16x32_bf16 v[16:19], v[180:183], v[204:207], v[16:19]
	v_mfma_f32_16x16x32_bf16 v[4:7], v[172:175], v[220:223], v[4:7]
	v_mfma_f32_16x16x32_bf16 v[0:3], v[180:183], v[220:223], v[0:3]
	v_mfma_f32_16x16x32_bf16 v[52:55], v[176:179], v[192:195], v[52:55]
	v_mfma_f32_16x16x32_bf16 v[48:51], v[184:187], v[192:195], v[48:51]
	v_mfma_f32_16x16x32_bf16 v[36:39], v[176:179], v[200:203], v[36:39]
	v_mfma_f32_16x16x32_bf16 v[32:35], v[184:187], v[200:203], v[32:35]
	v_mfma_f32_16x16x32_bf16 v[20:23], v[176:179], v[208:211], v[20:23]
	v_mfma_f32_16x16x32_bf16 v[16:19], v[184:187], v[208:211], v[16:19]
	v_mfma_f32_16x16x32_bf16 v[4:7], v[176:179], v[224:227], v[4:7]
	v_mfma_f32_16x16x32_bf16 v[0:3], v[184:187], v[224:227], v[0:3]
	s_nop 0
	s_barrier
	s_add_i32 s43, s43, 2
	s_add_u32 s0, s0, 0x100
	s_addc_u32 s1, s1, 0
	s_add_u32 s41, s41, 0x100
	s_addc_u32 s42, s42, 0
	s_cmp_gt_u32 s43, 29
	s_cbranch_scc0 .LBB0_503
	s_and_b64 vcc, exec, s[14:15]
	s_cbranch_vccz .LBB0_506
	s_barrier
